# scan consumer: the two rows of a lane share one 16-lane butterfly (first/second row roles swapped in the upper half of each DPP row): 5 DPP ops per step instead of 8
# speedup vs baseline: 1.0383x; 1.0082x over previous
; DEV void scan_tile(const Params& p, int l, int tile, char* smem) {
;     ...
;   const int r8 = lane >> 3, cg = lane & 7;
;   for (int ch = 0; ch < 136; ++ch) {
;     const int buf = ch & 1;
;     if (w < 4) {
;       const float* cb = arr + buf * 32 * 384;
;       const int vo = 320 + half * 32 + w * 8 + r8;
;       float* yw = ybuf + buf * 1024 + cg * 32 + w * 8 + r8;
;       auto ldops = [&](ScanOps& o, int sl) {
;         const f32x4* b4 = (const f32x4*)(cb + sl * 384);
;         o.nkk0 = b4[cg * 2]; o.nkk1 = b4[cg * 2 + 1];
;         o.w0 = b4[16 + cg * 2]; o.w1 = b4[16 + cg * 2 + 1];
;         o.kka0 = b4[32 + cg * 2]; o.kka1 = b4[32 + cg * 2 + 1];
;         o.kd0 = b4[48 + cg * 2]; o.kd1 = b4[48 + cg * 2 + 1];
;         o.r0 = b4[64 + cg * 2]; o.r1 = b4[64 + cg * 2 + 1];
;         o.v = cb[sl * 384 + vo];
;       };
;       float ykeep = 0.f;
;       auto step = [&](const ScanOps& o, int sl) {
;         const f32x4 sA = S0 * o.nkk0 + S1 * o.nkk1;
;         const float sa = red8((sA[0] + sA[1]) + (sA[2] + sA[3]));
;         S0 = S0 * o.w0 + (o.kka0 * sa + o.kd0 * o.v);
;         S1 = S1 * o.w1 + (o.kka1 * sa + o.kd1 * o.v);
;         const f32x4 yA = S0 * o.r0 + S1 * o.r1;
;         const float y = red8((yA[0] + yA[1]) + (yA[2] + yA[3]));
;         ykeep = (cg == (sl & 7)) ? y : ykeep;
;       };
.Lsc_consumer:
	v_and_b32_e32 v121, 15, v120
	v_lshrrev_b32_e32 v122, 4, v120
	s_lshl_b32 s58, s47, 3
	v_add_u32_e32 v122, s58, v122
	v_lshlrev_b32_e32 v78, 4, v121
	s_lshl_b32 s58, s30, 7
	v_lshl_add_u32 v79, v122, 2, s58
	v_lshlrev_b32_e32 v80, 7, v121
	v_lshl_add_u32 v80, v122, 2, v80
	v_add_u32_e32 v80, 0x18000, v80
	v_and_b32_e32 v123, 8, v121
	v_lshlrev_b32_e32 v123, 1, v123
	v_add_u32_e32 v79, v79, v123
	v_add_u32_e32 v80, v80, v123
	v_lshlrev_b32_e32 v123, 1, v123
	v_add_u32_e32 v81, 16, v79
	v_add_u32_e32 v82, 16, v80
	v_sub_u32_e32 v81, v81, v123
	v_sub_u32_e32 v82, v82, v123
	v_and_b32_e32 v123, 2, v121
	v_cmp_eq_u32_e64 s[62:63], 0, v123
	v_and_b32_e32 v123, 1, v121
	v_cmp_eq_u32_e64 s[64:65], 0, v123
	v_mov_b32_e32 v0, 0
	v_mov_b32_e32 v1, 0
	v_mov_b32_e32 v2, 0
	v_mov_b32_e32 v3, 0
	v_mov_b32_e32 v4, 0
	v_mov_b32_e32 v5, 0
	v_mov_b32_e32 v6, 0
	v_mov_b32_e32 v7, 0
	v_mov_b32_e32 v92, 0
	v_mov_b32_e32 v93, 0
	s_barrier
	s_barrier
.Lsc_cloop:
	ds_read_b128 v[8:11], v78 offset:0
	ds_read_b128 v[12:15], v78 offset:256
	ds_read_b128 v[16:19], v78 offset:512
	ds_read_b128 v[20:23], v78 offset:768
	ds_read_b128 v[24:27], v78 offset:1024
	ds_read2st64_b32 v[48:49], v79 offset0:5 offset1:11
	ds_read2st64_b32 v[52:53], v81 offset0:5 offset1:11
	s_waitcnt lgkmcnt(0)
	ds_read_b128 v[28:31], v78 offset:1536
	ds_read_b128 v[32:35], v78 offset:1792
	ds_read_b128 v[36:39], v78 offset:2048
	ds_read_b128 v[40:43], v78 offset:2304
	ds_read_b128 v[44:47], v78 offset:2560
	v_pk_mul_f32 v[56:57], v[0:1], v[8:9]
	v_pk_mul_f32 v[58:59], v[4:5], v[8:9]
	v_pk_fma_f32 v[56:57], v[2:3], v[10:11], v[56:57]
	v_pk_fma_f32 v[58:59], v[6:7], v[10:11], v[58:59]
	v_add_f32_e32 v72, v56, v57
	v_add_f32_e32 v73, v58, v59
	v_pk_mul_f32 v[64:65], v[20:21], v[48:49] op_sel_hi:[1,0]
	v_pk_mul_f32 v[68:69], v[20:21], v[52:53] op_sel_hi:[1,0]
	v_add_f32_dpp v74, v73, v72 row_mirror row_mask:0xf bank_mask:0xf bound_ctrl:1
	v_pk_mul_f32 v[66:67], v[22:23], v[48:49] op_sel_hi:[1,0]
	v_pk_mul_f32 v[70:71], v[22:23], v[52:53] op_sel_hi:[1,0]
	v_add_f32_dpp v74, v74, v74 quad_perm:[1,0,3,2] row_mask:0xf bank_mask:0xf bound_ctrl:1
	v_pk_fma_f32 v[0:1], v[0:1], v[12:13], v[64:65]
	v_pk_fma_f32 v[4:5], v[4:5], v[12:13], v[68:69]
	v_add_f32_dpp v74, v74, v74 quad_perm:[2,3,0,1] row_mask:0xf bank_mask:0xf bound_ctrl:1
	v_pk_fma_f32 v[2:3], v[2:3], v[14:15], v[66:67]
	v_pk_fma_f32 v[6:7], v[6:7], v[14:15], v[70:71]
	v_add_f32_dpp v74, v74, v74 row_half_mirror row_mask:0xf bank_mask:0xf bound_ctrl:1
	v_pk_fma_f32 v[0:1], v[16:17], v[74:75], v[0:1] op_sel_hi:[1,0,1]
	v_pk_fma_f32 v[2:3], v[18:19], v[74:75], v[2:3] op_sel_hi:[1,0,1]
	v_mov_b32_dpp v76, v74 row_mirror row_mask:0xf bank_mask:0xf bound_ctrl:1
	v_pk_mul_f32 v[60:61], v[0:1], v[24:25]
	v_pk_fma_f32 v[4:5], v[16:17], v[76:77], v[4:5] op_sel_hi:[1,0,1]
	v_pk_fma_f32 v[6:7], v[18:19], v[76:77], v[6:7] op_sel_hi:[1,0,1]
	v_pk_fma_f32 v[60:61], v[2:3], v[26:27], v[60:61]
	v_pk_mul_f32 v[62:63], v[4:5], v[24:25]
	v_pk_fma_f32 v[62:63], v[6:7], v[26:27], v[62:63]
	v_add_f32_e32 v98, v60, v61
	v_add_f32_e32 v114, v62, v63
	s_waitcnt lgkmcnt(0)
	ds_read_b128 v[8:11], v78 offset:3072
	ds_read_b128 v[12:15], v78 offset:3328
	ds_read_b128 v[16:19], v78 offset:3584
	ds_read_b128 v[20:23], v78 offset:3840
	ds_read_b128 v[24:27], v78 offset:4096
	ds_read2st64_b32 v[50:51], v79 offset0:17 offset1:23
	ds_read2st64_b32 v[54:55], v81 offset0:17 offset1:23
	v_pk_mul_f32 v[56:57], v[0:1], v[28:29]
	v_pk_mul_f32 v[58:59], v[4:5], v[28:29]
	v_pk_fma_f32 v[56:57], v[2:3], v[30:31], v[56:57]
	v_pk_fma_f32 v[58:59], v[6:7], v[30:31], v[58:59]
	v_add_f32_e32 v72, v56, v57
	v_add_f32_e32 v73, v58, v59
	v_pk_mul_f32 v[64:65], v[40:41], v[48:49] op_sel:[0,1] op_sel_hi:[1,1]
	v_pk_mul_f32 v[68:69], v[40:41], v[52:53] op_sel:[0,1] op_sel_hi:[1,1]
	v_add_f32_dpp v74, v73, v72 row_mirror row_mask:0xf bank_mask:0xf bound_ctrl:1
	v_pk_mul_f32 v[66:67], v[42:43], v[48:49] op_sel:[0,1] op_sel_hi:[1,1]
	v_pk_mul_f32 v[70:71], v[42:43], v[52:53] op_sel:[0,1] op_sel_hi:[1,1]
	v_add_f32_dpp v74, v74, v74 quad_perm:[1,0,3,2] row_mask:0xf bank_mask:0xf bound_ctrl:1
	v_pk_fma_f32 v[0:1], v[0:1], v[32:33], v[64:65]
	v_pk_fma_f32 v[4:5], v[4:5], v[32:33], v[68:69]
	v_add_f32_dpp v74, v74, v74 quad_perm:[2,3,0,1] row_mask:0xf bank_mask:0xf bound_ctrl:1
	v_pk_fma_f32 v[2:3], v[2:3], v[34:35], v[66:67]
	v_pk_fma_f32 v[6:7], v[6:7], v[34:35], v[70:71]
	v_add_f32_dpp v74, v74, v74 row_half_mirror row_mask:0xf bank_mask:0xf bound_ctrl:1
	v_pk_fma_f32 v[0:1], v[36:37], v[74:75], v[0:1] op_sel_hi:[1,0,1]
	v_pk_fma_f32 v[2:3], v[38:39], v[74:75], v[2:3] op_sel_hi:[1,0,1]
	v_mov_b32_dpp v76, v74 row_mirror row_mask:0xf bank_mask:0xf bound_ctrl:1
	v_pk_mul_f32 v[60:61], v[0:1], v[44:45]
	v_pk_fma_f32 v[4:5], v[36:37], v[76:77], v[4:5] op_sel_hi:[1,0,1]
	v_pk_fma_f32 v[6:7], v[38:39], v[76:77], v[6:7] op_sel_hi:[1,0,1]
	v_pk_fma_f32 v[60:61], v[2:3], v[46:47], v[60:61]
	v_pk_mul_f32 v[62:63], v[4:5], v[44:45]
	v_pk_fma_f32 v[62:63], v[6:7], v[46:47], v[62:63]
	v_add_f32_e32 v99, v60, v61
	v_add_f32_e32 v115, v62, v63
	s_waitcnt lgkmcnt(0)
; DEV void scan_tile(const Params& p, int l, int tile, char* smem) {
;     ...
;       auto ldops = [&](ScanOps& o, int sl) {
;         const f32x4* b4 = (const f32x4*)(cb + sl * 384);
;         o.nkk0 = b4[cg * 2]; o.nkk1 = b4[cg * 2 + 1];
;         o.w0 = b4[16 + cg * 2]; o.w1 = b4[16 + cg * 2 + 1];
;         o.kka0 = b4[32 + cg * 2]; o.kka1 = b4[32 + cg * 2 + 1];
;         o.kd0 = b4[48 + cg * 2]; o.kd1 = b4[48 + cg * 2 + 1];
;         o.r0 = b4[64 + cg * 2]; o.r1 = b4[64 + cg * 2 + 1];
;         o.v = cb[sl * 384 + vo];
;       };
;       float ykeep = 0.f;
;       auto step = [&](const ScanOps& o, int sl) {
;         const f32x4 sA = S0 * o.nkk0 + S1 * o.nkk1;
;         const float sa = red8((sA[0] + sA[1]) + (sA[2] + sA[3]));
;         S0 = S0 * o.w0 + (o.kka0 * sa + o.kd0 * o.v);
;         S1 = S1 * o.w1 + (o.kka1 * sa + o.kd1 * o.v);
;         const f32x4 yA = S0 * o.r0 + S1 * o.r1;
;         const float y = red8((yA[0] + yA[1]) + (yA[2] + yA[3]));
;         ykeep = (cg == (sl & 7)) ? y : ykeep;
;       };
	ds_read_b128 v[28:31], v78 offset:4608
	ds_read_b128 v[32:35], v78 offset:4864
	ds_read_b128 v[36:39], v78 offset:5120
	ds_read_b128 v[40:43], v78 offset:5376
	ds_read_b128 v[44:47], v78 offset:5632
	v_pk_mul_f32 v[56:57], v[0:1], v[8:9]
	v_pk_mul_f32 v[58:59], v[4:5], v[8:9]
	v_pk_fma_f32 v[56:57], v[2:3], v[10:11], v[56:57]
	v_pk_fma_f32 v[58:59], v[6:7], v[10:11], v[58:59]
	v_add_f32_e32 v72, v56, v57
	v_add_f32_e32 v73, v58, v59
	v_pk_mul_f32 v[64:65], v[20:21], v[50:51] op_sel_hi:[1,0]
	v_pk_mul_f32 v[68:69], v[20:21], v[54:55] op_sel_hi:[1,0]
	v_add_f32_dpp v74, v73, v72 row_mirror row_mask:0xf bank_mask:0xf bound_ctrl:1
	v_pk_mul_f32 v[66:67], v[22:23], v[50:51] op_sel_hi:[1,0]
	v_pk_mul_f32 v[70:71], v[22:23], v[54:55] op_sel_hi:[1,0]
	v_add_f32_dpp v74, v74, v74 quad_perm:[1,0,3,2] row_mask:0xf bank_mask:0xf bound_ctrl:1
	v_pk_fma_f32 v[0:1], v[0:1], v[12:13], v[64:65]
	v_pk_fma_f32 v[4:5], v[4:5], v[12:13], v[68:69]
	v_add_f32_dpp v74, v74, v74 quad_perm:[2,3,0,1] row_mask:0xf bank_mask:0xf bound_ctrl:1
	v_pk_fma_f32 v[2:3], v[2:3], v[14:15], v[66:67]
	v_pk_fma_f32 v[6:7], v[6:7], v[14:15], v[70:71]
	v_add_f32_dpp v74, v74, v74 row_half_mirror row_mask:0xf bank_mask:0xf bound_ctrl:1
	v_pk_fma_f32 v[0:1], v[16:17], v[74:75], v[0:1] op_sel_hi:[1,0,1]
	v_pk_fma_f32 v[2:3], v[18:19], v[74:75], v[2:3] op_sel_hi:[1,0,1]
	v_mov_b32_dpp v76, v74 row_mirror row_mask:0xf bank_mask:0xf bound_ctrl:1
	v_pk_mul_f32 v[60:61], v[0:1], v[24:25]
	v_pk_fma_f32 v[4:5], v[16:17], v[76:77], v[4:5] op_sel_hi:[1,0,1]
	v_pk_fma_f32 v[6:7], v[18:19], v[76:77], v[6:7] op_sel_hi:[1,0,1]
	v_pk_fma_f32 v[60:61], v[2:3], v[26:27], v[60:61]
	v_pk_mul_f32 v[62:63], v[4:5], v[24:25]
	v_pk_fma_f32 v[62:63], v[6:7], v[26:27], v[62:63]
	v_add_f32_e32 v100, v60, v61
	v_add_f32_e32 v116, v62, v63
	s_waitcnt lgkmcnt(0)
	ds_read_b128 v[8:11], v78 offset:6144
	ds_read_b128 v[12:15], v78 offset:6400
	ds_read_b128 v[16:19], v78 offset:6656
	ds_read_b128 v[20:23], v78 offset:6912
	ds_read_b128 v[24:27], v78 offset:7168
	ds_read2st64_b32 v[48:49], v79 offset0:29 offset1:35
	ds_read2st64_b32 v[52:53], v81 offset0:29 offset1:35
	v_pk_mul_f32 v[56:57], v[0:1], v[28:29]
	v_pk_mul_f32 v[58:59], v[4:5], v[28:29]
	v_pk_fma_f32 v[56:57], v[2:3], v[30:31], v[56:57]
	v_pk_fma_f32 v[58:59], v[6:7], v[30:31], v[58:59]
	v_add_f32_e32 v72, v56, v57
	v_add_f32_e32 v73, v58, v59
	v_pk_mul_f32 v[64:65], v[40:41], v[50:51] op_sel:[0,1] op_sel_hi:[1,1]
	v_pk_mul_f32 v[68:69], v[40:41], v[54:55] op_sel:[0,1] op_sel_hi:[1,1]
	v_add_f32_dpp v74, v73, v72 row_mirror row_mask:0xf bank_mask:0xf bound_ctrl:1
	v_pk_mul_f32 v[66:67], v[42:43], v[50:51] op_sel:[0,1] op_sel_hi:[1,1]
	v_pk_mul_f32 v[70:71], v[42:43], v[54:55] op_sel:[0,1] op_sel_hi:[1,1]
	v_add_f32_dpp v74, v74, v74 quad_perm:[1,0,3,2] row_mask:0xf bank_mask:0xf bound_ctrl:1
	v_pk_fma_f32 v[0:1], v[0:1], v[32:33], v[64:65]
	v_pk_fma_f32 v[4:5], v[4:5], v[32:33], v[68:69]
	v_add_f32_dpp v74, v74, v74 quad_perm:[2,3,0,1] row_mask:0xf bank_mask:0xf bound_ctrl:1
	v_pk_fma_f32 v[2:3], v[2:3], v[34:35], v[66:67]
	v_pk_fma_f32 v[6:7], v[6:7], v[34:35], v[70:71]
	v_add_f32_dpp v74, v74, v74 row_half_mirror row_mask:0xf bank_mask:0xf bound_ctrl:1
	v_pk_fma_f32 v[0:1], v[36:37], v[74:75], v[0:1] op_sel_hi:[1,0,1]
	v_pk_fma_f32 v[2:3], v[38:39], v[74:75], v[2:3] op_sel_hi:[1,0,1]
	v_mov_b32_dpp v76, v74 row_mirror row_mask:0xf bank_mask:0xf bound_ctrl:1
	v_pk_mul_f32 v[60:61], v[0:1], v[44:45]
	v_pk_fma_f32 v[4:5], v[36:37], v[76:77], v[4:5] op_sel_hi:[1,0,1]
	v_pk_fma_f32 v[6:7], v[38:39], v[76:77], v[6:7] op_sel_hi:[1,0,1]
	v_pk_fma_f32 v[60:61], v[2:3], v[46:47], v[60:61]
	v_pk_mul_f32 v[62:63], v[4:5], v[44:45]
	v_pk_fma_f32 v[62:63], v[6:7], v[46:47], v[62:63]
	v_add_f32_e32 v101, v60, v61
	v_add_f32_e32 v117, v62, v63
	s_waitcnt lgkmcnt(0)
	ds_read_b128 v[28:31], v78 offset:7680
	ds_read_b128 v[32:35], v78 offset:7936
	ds_read_b128 v[36:39], v78 offset:8192
	ds_read_b128 v[40:43], v78 offset:8448
	ds_read_b128 v[44:47], v78 offset:8704
	v_pk_mul_f32 v[56:57], v[0:1], v[8:9]
	v_pk_mul_f32 v[58:59], v[4:5], v[8:9]
	v_pk_fma_f32 v[56:57], v[2:3], v[10:11], v[56:57]
	v_pk_fma_f32 v[58:59], v[6:7], v[10:11], v[58:59]
	v_add_f32_e32 v72, v56, v57
	v_add_f32_e32 v73, v58, v59
	v_pk_mul_f32 v[64:65], v[20:21], v[48:49] op_sel_hi:[1,0]
	v_pk_mul_f32 v[68:69], v[20:21], v[52:53] op_sel_hi:[1,0]
	v_add_f32_dpp v74, v73, v72 row_mirror row_mask:0xf bank_mask:0xf bound_ctrl:1
	v_pk_mul_f32 v[66:67], v[22:23], v[48:49] op_sel_hi:[1,0]
	v_pk_mul_f32 v[70:71], v[22:23], v[52:53] op_sel_hi:[1,0]
	v_add_f32_dpp v74, v74, v74 quad_perm:[1,0,3,2] row_mask:0xf bank_mask:0xf bound_ctrl:1
	v_pk_fma_f32 v[0:1], v[0:1], v[12:13], v[64:65]
	v_pk_fma_f32 v[4:5], v[4:5], v[12:13], v[68:69]
	v_add_f32_dpp v74, v74, v74 quad_perm:[2,3,0,1] row_mask:0xf bank_mask:0xf bound_ctrl:1
	v_pk_fma_f32 v[2:3], v[2:3], v[14:15], v[66:67]
	v_pk_fma_f32 v[6:7], v[6:7], v[14:15], v[70:71]
	v_add_f32_dpp v74, v74, v74 row_half_mirror row_mask:0xf bank_mask:0xf bound_ctrl:1
	v_pk_fma_f32 v[0:1], v[16:17], v[74:75], v[0:1] op_sel_hi:[1,0,1]
	v_pk_fma_f32 v[2:3], v[18:19], v[74:75], v[2:3] op_sel_hi:[1,0,1]
	v_mov_b32_dpp v76, v74 row_mirror row_mask:0xf bank_mask:0xf bound_ctrl:1
	v_pk_mul_f32 v[60:61], v[0:1], v[24:25]
	v_pk_fma_f32 v[4:5], v[16:17], v[76:77], v[4:5] op_sel_hi:[1,0,1]
	v_pk_fma_f32 v[6:7], v[18:19], v[76:77], v[6:7] op_sel_hi:[1,0,1]
	v_pk_fma_f32 v[60:61], v[2:3], v[26:27], v[60:61]
	v_pk_mul_f32 v[62:63], v[4:5], v[24:25]
	v_pk_fma_f32 v[62:63], v[6:7], v[26:27], v[62:63]
	v_add_f32_e32 v102, v60, v61
	v_add_f32_e32 v118, v62, v63
	s_waitcnt lgkmcnt(0)
; DEV void scan_tile(const Params& p, int l, int tile, char* smem) {
;     ...
;       auto ldops = [&](ScanOps& o, int sl) {
;         const f32x4* b4 = (const f32x4*)(cb + sl * 384);
;         o.nkk0 = b4[cg * 2]; o.nkk1 = b4[cg * 2 + 1];
;         o.w0 = b4[16 + cg * 2]; o.w1 = b4[16 + cg * 2 + 1];
;         o.kka0 = b4[32 + cg * 2]; o.kka1 = b4[32 + cg * 2 + 1];
;         o.kd0 = b4[48 + cg * 2]; o.kd1 = b4[48 + cg * 2 + 1];
;         o.r0 = b4[64 + cg * 2]; o.r1 = b4[64 + cg * 2 + 1];
;         o.v = cb[sl * 384 + vo];
;       };
;       float ykeep = 0.f;
;       auto step = [&](const ScanOps& o, int sl) {
;         const f32x4 sA = S0 * o.nkk0 + S1 * o.nkk1;
;         const float sa = red8((sA[0] + sA[1]) + (sA[2] + sA[3]));
;         S0 = S0 * o.w0 + (o.kka0 * sa + o.kd0 * o.v);
;         S1 = S1 * o.w1 + (o.kka1 * sa + o.kd1 * o.v);
;         const f32x4 yA = S0 * o.r0 + S1 * o.r1;
;         const float y = red8((yA[0] + yA[1]) + (yA[2] + yA[3]));
;         ykeep = (cg == (sl & 7)) ? y : ykeep;
;       };
	ds_read_b128 v[8:11], v78 offset:9216
	ds_read_b128 v[12:15], v78 offset:9472
	ds_read_b128 v[16:19], v78 offset:9728
	ds_read_b128 v[20:23], v78 offset:9984
	ds_read_b128 v[24:27], v78 offset:10240
	ds_read2st64_b32 v[50:51], v79 offset0:41 offset1:47
	ds_read2st64_b32 v[54:55], v81 offset0:41 offset1:47
	v_pk_mul_f32 v[56:57], v[0:1], v[28:29]
	v_pk_mul_f32 v[58:59], v[4:5], v[28:29]
	v_pk_fma_f32 v[56:57], v[2:3], v[30:31], v[56:57]
	v_pk_fma_f32 v[58:59], v[6:7], v[30:31], v[58:59]
	v_add_f32_e32 v72, v56, v57
	v_add_f32_e32 v73, v58, v59
	v_pk_mul_f32 v[64:65], v[40:41], v[48:49] op_sel:[0,1] op_sel_hi:[1,1]
	v_pk_mul_f32 v[68:69], v[40:41], v[52:53] op_sel:[0,1] op_sel_hi:[1,1]
	v_add_f32_dpp v74, v73, v72 row_mirror row_mask:0xf bank_mask:0xf bound_ctrl:1
	v_pk_mul_f32 v[66:67], v[42:43], v[48:49] op_sel:[0,1] op_sel_hi:[1,1]
	v_pk_mul_f32 v[70:71], v[42:43], v[52:53] op_sel:[0,1] op_sel_hi:[1,1]
	v_add_f32_dpp v74, v74, v74 quad_perm:[1,0,3,2] row_mask:0xf bank_mask:0xf bound_ctrl:1
	v_pk_fma_f32 v[0:1], v[0:1], v[32:33], v[64:65]
	v_pk_fma_f32 v[4:5], v[4:5], v[32:33], v[68:69]
	v_add_f32_dpp v74, v74, v74 quad_perm:[2,3,0,1] row_mask:0xf bank_mask:0xf bound_ctrl:1
	v_pk_fma_f32 v[2:3], v[2:3], v[34:35], v[66:67]
	v_pk_fma_f32 v[6:7], v[6:7], v[34:35], v[70:71]
	v_add_f32_dpp v74, v74, v74 row_half_mirror row_mask:0xf bank_mask:0xf bound_ctrl:1
	v_pk_fma_f32 v[0:1], v[36:37], v[74:75], v[0:1] op_sel_hi:[1,0,1]
	v_pk_fma_f32 v[2:3], v[38:39], v[74:75], v[2:3] op_sel_hi:[1,0,1]
	v_mov_b32_dpp v76, v74 row_mirror row_mask:0xf bank_mask:0xf bound_ctrl:1
	v_pk_mul_f32 v[60:61], v[0:1], v[44:45]
	v_pk_fma_f32 v[4:5], v[36:37], v[76:77], v[4:5] op_sel_hi:[1,0,1]
	v_pk_fma_f32 v[6:7], v[38:39], v[76:77], v[6:7] op_sel_hi:[1,0,1]
	v_pk_fma_f32 v[60:61], v[2:3], v[46:47], v[60:61]
	v_pk_mul_f32 v[62:63], v[4:5], v[44:45]
	v_pk_fma_f32 v[62:63], v[6:7], v[46:47], v[62:63]
	v_add_f32_e32 v103, v60, v61
	v_add_f32_e32 v119, v62, v63
	s_waitcnt lgkmcnt(0)
	ds_read_b128 v[28:31], v78 offset:10752
	ds_read_b128 v[32:35], v78 offset:11008
	ds_read_b128 v[36:39], v78 offset:11264
	ds_read_b128 v[40:43], v78 offset:11520
	ds_read_b128 v[44:47], v78 offset:11776
	v_pk_mul_f32 v[56:57], v[0:1], v[8:9]
	v_pk_mul_f32 v[58:59], v[4:5], v[8:9]
	v_pk_fma_f32 v[56:57], v[2:3], v[10:11], v[56:57]
	v_pk_fma_f32 v[58:59], v[6:7], v[10:11], v[58:59]
	v_add_f32_e32 v72, v56, v57
	v_add_f32_e32 v73, v58, v59
	v_pk_mul_f32 v[64:65], v[20:21], v[50:51] op_sel_hi:[1,0]
	v_pk_mul_f32 v[68:69], v[20:21], v[54:55] op_sel_hi:[1,0]
	v_add_f32_dpp v74, v73, v72 row_mirror row_mask:0xf bank_mask:0xf bound_ctrl:1
	v_pk_mul_f32 v[66:67], v[22:23], v[50:51] op_sel_hi:[1,0]
	v_pk_mul_f32 v[70:71], v[22:23], v[54:55] op_sel_hi:[1,0]
	v_add_f32_dpp v74, v74, v74 quad_perm:[1,0,3,2] row_mask:0xf bank_mask:0xf bound_ctrl:1
	v_pk_fma_f32 v[0:1], v[0:1], v[12:13], v[64:65]
	v_pk_fma_f32 v[4:5], v[4:5], v[12:13], v[68:69]
	v_add_f32_dpp v74, v74, v74 quad_perm:[2,3,0,1] row_mask:0xf bank_mask:0xf bound_ctrl:1
	v_pk_fma_f32 v[2:3], v[2:3], v[14:15], v[66:67]
	v_pk_fma_f32 v[6:7], v[6:7], v[14:15], v[70:71]
	v_add_f32_dpp v74, v74, v74 row_half_mirror row_mask:0xf bank_mask:0xf bound_ctrl:1
	v_pk_fma_f32 v[0:1], v[16:17], v[74:75], v[0:1] op_sel_hi:[1,0,1]
	v_pk_fma_f32 v[2:3], v[18:19], v[74:75], v[2:3] op_sel_hi:[1,0,1]
	v_mov_b32_dpp v76, v74 row_mirror row_mask:0xf bank_mask:0xf bound_ctrl:1
	v_pk_mul_f32 v[60:61], v[0:1], v[24:25]
	v_pk_fma_f32 v[4:5], v[16:17], v[76:77], v[4:5] op_sel_hi:[1,0,1]
	v_pk_fma_f32 v[6:7], v[18:19], v[76:77], v[6:7] op_sel_hi:[1,0,1]
	v_pk_fma_f32 v[60:61], v[2:3], v[26:27], v[60:61]
	v_pk_mul_f32 v[62:63], v[4:5], v[24:25]
	v_pk_fma_f32 v[62:63], v[6:7], v[26:27], v[62:63]
	v_add_f32_e32 v104, v60, v61
	v_add_f32_e32 v120, v62, v63
	s_waitcnt lgkmcnt(0)
	ds_read_b128 v[8:11], v78 offset:12288
	ds_read_b128 v[12:15], v78 offset:12544
	ds_read_b128 v[16:19], v78 offset:12800
	ds_read_b128 v[20:23], v78 offset:13056
	ds_read_b128 v[24:27], v78 offset:13312
	ds_read2st64_b32 v[48:49], v79 offset0:53 offset1:59
	ds_read2st64_b32 v[52:53], v81 offset0:53 offset1:59
	v_pk_mul_f32 v[56:57], v[0:1], v[28:29]
	v_pk_mul_f32 v[58:59], v[4:5], v[28:29]
	v_pk_fma_f32 v[56:57], v[2:3], v[30:31], v[56:57]
	v_pk_fma_f32 v[58:59], v[6:7], v[30:31], v[58:59]
	v_add_f32_e32 v72, v56, v57
	v_add_f32_e32 v73, v58, v59
	v_pk_mul_f32 v[64:65], v[40:41], v[50:51] op_sel:[0,1] op_sel_hi:[1,1]
	v_pk_mul_f32 v[68:69], v[40:41], v[54:55] op_sel:[0,1] op_sel_hi:[1,1]
	v_add_f32_dpp v74, v73, v72 row_mirror row_mask:0xf bank_mask:0xf bound_ctrl:1
	v_pk_mul_f32 v[66:67], v[42:43], v[50:51] op_sel:[0,1] op_sel_hi:[1,1]
	v_pk_mul_f32 v[70:71], v[42:43], v[54:55] op_sel:[0,1] op_sel_hi:[1,1]
	v_add_f32_dpp v74, v74, v74 quad_perm:[1,0,3,2] row_mask:0xf bank_mask:0xf bound_ctrl:1
	v_pk_fma_f32 v[0:1], v[0:1], v[32:33], v[64:65]
	v_pk_fma_f32 v[4:5], v[4:5], v[32:33], v[68:69]
	v_add_f32_dpp v74, v74, v74 quad_perm:[2,3,0,1] row_mask:0xf bank_mask:0xf bound_ctrl:1
	v_pk_fma_f32 v[2:3], v[2:3], v[34:35], v[66:67]
	v_pk_fma_f32 v[6:7], v[6:7], v[34:35], v[70:71]
	v_add_f32_dpp v74, v74, v74 row_half_mirror row_mask:0xf bank_mask:0xf bound_ctrl:1
	v_pk_fma_f32 v[0:1], v[36:37], v[74:75], v[0:1] op_sel_hi:[1,0,1]
	v_pk_fma_f32 v[2:3], v[38:39], v[74:75], v[2:3] op_sel_hi:[1,0,1]
	v_mov_b32_dpp v76, v74 row_mirror row_mask:0xf bank_mask:0xf bound_ctrl:1
	v_pk_mul_f32 v[60:61], v[0:1], v[44:45]
	v_pk_fma_f32 v[4:5], v[36:37], v[76:77], v[4:5] op_sel_hi:[1,0,1]
	v_pk_fma_f32 v[6:7], v[38:39], v[76:77], v[6:7] op_sel_hi:[1,0,1]
	v_pk_fma_f32 v[60:61], v[2:3], v[46:47], v[60:61]
	v_pk_mul_f32 v[62:63], v[4:5], v[44:45]
	v_pk_fma_f32 v[62:63], v[6:7], v[46:47], v[62:63]
	v_add_f32_e32 v105, v60, v61
	v_add_f32_e32 v121, v62, v63
	s_waitcnt lgkmcnt(0)
; DEV void scan_tile(const Params& p, int l, int tile, char* smem) {
;     ...
;       auto ldops = [&](ScanOps& o, int sl) {
;         const f32x4* b4 = (const f32x4*)(cb + sl * 384);
;         o.nkk0 = b4[cg * 2]; o.nkk1 = b4[cg * 2 + 1];
;         o.w0 = b4[16 + cg * 2]; o.w1 = b4[16 + cg * 2 + 1];
;         o.kka0 = b4[32 + cg * 2]; o.kka1 = b4[32 + cg * 2 + 1];
;         o.kd0 = b4[48 + cg * 2]; o.kd1 = b4[48 + cg * 2 + 1];
;         o.r0 = b4[64 + cg * 2]; o.r1 = b4[64 + cg * 2 + 1];
;         o.v = cb[sl * 384 + vo];
;       };
;       float ykeep = 0.f;
;       auto step = [&](const ScanOps& o, int sl) {
;         const f32x4 sA = S0 * o.nkk0 + S1 * o.nkk1;
;         const float sa = red8((sA[0] + sA[1]) + (sA[2] + sA[3]));
;         S0 = S0 * o.w0 + (o.kka0 * sa + o.kd0 * o.v);
;         S1 = S1 * o.w1 + (o.kka1 * sa + o.kd1 * o.v);
;         const f32x4 yA = S0 * o.r0 + S1 * o.r1;
;         const float y = red8((yA[0] + yA[1]) + (yA[2] + yA[3]));
;         ykeep = (cg == (sl & 7)) ? y : ykeep;
;       };
	ds_read_b128 v[28:31], v78 offset:13824
	ds_read_b128 v[32:35], v78 offset:14080
	ds_read_b128 v[36:39], v78 offset:14336
	ds_read_b128 v[40:43], v78 offset:14592
	ds_read_b128 v[44:47], v78 offset:14848
	v_pk_mul_f32 v[56:57], v[0:1], v[8:9]
	v_pk_mul_f32 v[58:59], v[4:5], v[8:9]
	v_pk_fma_f32 v[56:57], v[2:3], v[10:11], v[56:57]
	v_pk_fma_f32 v[58:59], v[6:7], v[10:11], v[58:59]
	v_add_f32_e32 v72, v56, v57
	v_add_f32_e32 v73, v58, v59
	v_pk_mul_f32 v[64:65], v[20:21], v[48:49] op_sel_hi:[1,0]
	v_pk_mul_f32 v[68:69], v[20:21], v[52:53] op_sel_hi:[1,0]
	v_add_f32_dpp v74, v73, v72 row_mirror row_mask:0xf bank_mask:0xf bound_ctrl:1
	v_pk_mul_f32 v[66:67], v[22:23], v[48:49] op_sel_hi:[1,0]
	v_pk_mul_f32 v[70:71], v[22:23], v[52:53] op_sel_hi:[1,0]
	v_add_f32_dpp v74, v74, v74 quad_perm:[1,0,3,2] row_mask:0xf bank_mask:0xf bound_ctrl:1
	v_pk_fma_f32 v[0:1], v[0:1], v[12:13], v[64:65]
	v_pk_fma_f32 v[4:5], v[4:5], v[12:13], v[68:69]
	v_add_f32_dpp v74, v74, v74 quad_perm:[2,3,0,1] row_mask:0xf bank_mask:0xf bound_ctrl:1
	v_pk_fma_f32 v[2:3], v[2:3], v[14:15], v[66:67]
	v_pk_fma_f32 v[6:7], v[6:7], v[14:15], v[70:71]
	v_add_f32_dpp v74, v74, v74 row_half_mirror row_mask:0xf bank_mask:0xf bound_ctrl:1
	v_pk_fma_f32 v[0:1], v[16:17], v[74:75], v[0:1] op_sel_hi:[1,0,1]
	v_pk_fma_f32 v[2:3], v[18:19], v[74:75], v[2:3] op_sel_hi:[1,0,1]
	v_mov_b32_dpp v76, v74 row_mirror row_mask:0xf bank_mask:0xf bound_ctrl:1
	v_pk_mul_f32 v[60:61], v[0:1], v[24:25]
	v_pk_fma_f32 v[4:5], v[16:17], v[76:77], v[4:5] op_sel_hi:[1,0,1]
	v_pk_fma_f32 v[6:7], v[18:19], v[76:77], v[6:7] op_sel_hi:[1,0,1]
	v_pk_fma_f32 v[60:61], v[2:3], v[26:27], v[60:61]
	v_pk_mul_f32 v[62:63], v[4:5], v[24:25]
	v_pk_fma_f32 v[62:63], v[6:7], v[26:27], v[62:63]
	v_add_f32_e32 v106, v60, v61
	v_add_f32_e32 v122, v62, v63
	s_waitcnt lgkmcnt(0)
	ds_read_b128 v[8:11], v78 offset:15360
	ds_read_b128 v[12:15], v78 offset:15616
	ds_read_b128 v[16:19], v78 offset:15872
	ds_read_b128 v[20:23], v78 offset:16128
	ds_read_b128 v[24:27], v78 offset:16384
	ds_read2st64_b32 v[50:51], v79 offset0:65 offset1:71
	ds_read2st64_b32 v[54:55], v81 offset0:65 offset1:71
	v_pk_mul_f32 v[56:57], v[0:1], v[28:29]
	v_pk_mul_f32 v[58:59], v[4:5], v[28:29]
	v_pk_fma_f32 v[56:57], v[2:3], v[30:31], v[56:57]
	v_pk_fma_f32 v[58:59], v[6:7], v[30:31], v[58:59]
	v_add_f32_e32 v72, v56, v57
	v_add_f32_e32 v73, v58, v59
	v_pk_mul_f32 v[64:65], v[40:41], v[48:49] op_sel:[0,1] op_sel_hi:[1,1]
	v_pk_mul_f32 v[68:69], v[40:41], v[52:53] op_sel:[0,1] op_sel_hi:[1,1]
	v_add_f32_dpp v74, v73, v72 row_mirror row_mask:0xf bank_mask:0xf bound_ctrl:1
	v_pk_mul_f32 v[66:67], v[42:43], v[48:49] op_sel:[0,1] op_sel_hi:[1,1]
	v_pk_mul_f32 v[70:71], v[42:43], v[52:53] op_sel:[0,1] op_sel_hi:[1,1]
	v_add_f32_dpp v74, v74, v74 quad_perm:[1,0,3,2] row_mask:0xf bank_mask:0xf bound_ctrl:1
	v_pk_fma_f32 v[0:1], v[0:1], v[32:33], v[64:65]
	v_pk_fma_f32 v[4:5], v[4:5], v[32:33], v[68:69]
	v_add_f32_dpp v74, v74, v74 quad_perm:[2,3,0,1] row_mask:0xf bank_mask:0xf bound_ctrl:1
	v_pk_fma_f32 v[2:3], v[2:3], v[34:35], v[66:67]
	v_pk_fma_f32 v[6:7], v[6:7], v[34:35], v[70:71]
	v_add_f32_dpp v74, v74, v74 row_half_mirror row_mask:0xf bank_mask:0xf bound_ctrl:1
	v_pk_fma_f32 v[0:1], v[36:37], v[74:75], v[0:1] op_sel_hi:[1,0,1]
	v_pk_fma_f32 v[2:3], v[38:39], v[74:75], v[2:3] op_sel_hi:[1,0,1]
	v_mov_b32_dpp v76, v74 row_mirror row_mask:0xf bank_mask:0xf bound_ctrl:1
	v_pk_mul_f32 v[60:61], v[0:1], v[44:45]
	v_pk_fma_f32 v[4:5], v[36:37], v[76:77], v[4:5] op_sel_hi:[1,0,1]
	v_pk_fma_f32 v[6:7], v[38:39], v[76:77], v[6:7] op_sel_hi:[1,0,1]
	v_pk_fma_f32 v[60:61], v[2:3], v[46:47], v[60:61]
	v_pk_mul_f32 v[62:63], v[4:5], v[44:45]
	v_pk_fma_f32 v[62:63], v[6:7], v[46:47], v[62:63]
	v_add_f32_e32 v107, v60, v61
	v_add_f32_e32 v123, v62, v63
	s_waitcnt lgkmcnt(0)
	ds_read_b128 v[28:31], v78 offset:16896
	ds_read_b128 v[32:35], v78 offset:17152
	ds_read_b128 v[36:39], v78 offset:17408
	ds_read_b128 v[40:43], v78 offset:17664
	ds_read_b128 v[44:47], v78 offset:17920
	v_pk_mul_f32 v[56:57], v[0:1], v[8:9]
	v_pk_mul_f32 v[58:59], v[4:5], v[8:9]
	v_pk_fma_f32 v[56:57], v[2:3], v[10:11], v[56:57]
	v_pk_fma_f32 v[58:59], v[6:7], v[10:11], v[58:59]
	v_add_f32_e32 v72, v56, v57
	v_add_f32_e32 v73, v58, v59
	v_pk_mul_f32 v[64:65], v[20:21], v[50:51] op_sel_hi:[1,0]
	v_pk_mul_f32 v[68:69], v[20:21], v[54:55] op_sel_hi:[1,0]
	v_add_f32_dpp v74, v73, v72 row_mirror row_mask:0xf bank_mask:0xf bound_ctrl:1
	v_pk_mul_f32 v[66:67], v[22:23], v[50:51] op_sel_hi:[1,0]
	v_pk_mul_f32 v[70:71], v[22:23], v[54:55] op_sel_hi:[1,0]
	v_add_f32_dpp v74, v74, v74 quad_perm:[1,0,3,2] row_mask:0xf bank_mask:0xf bound_ctrl:1
	v_pk_fma_f32 v[0:1], v[0:1], v[12:13], v[64:65]
	v_pk_fma_f32 v[4:5], v[4:5], v[12:13], v[68:69]
	v_add_f32_dpp v74, v74, v74 quad_perm:[2,3,0,1] row_mask:0xf bank_mask:0xf bound_ctrl:1
	v_pk_fma_f32 v[2:3], v[2:3], v[14:15], v[66:67]
	v_pk_fma_f32 v[6:7], v[6:7], v[14:15], v[70:71]
	v_add_f32_dpp v74, v74, v74 row_half_mirror row_mask:0xf bank_mask:0xf bound_ctrl:1
	v_pk_fma_f32 v[0:1], v[16:17], v[74:75], v[0:1] op_sel_hi:[1,0,1]
	v_pk_fma_f32 v[2:3], v[18:19], v[74:75], v[2:3] op_sel_hi:[1,0,1]
	v_mov_b32_dpp v76, v74 row_mirror row_mask:0xf bank_mask:0xf bound_ctrl:1
	v_pk_mul_f32 v[60:61], v[0:1], v[24:25]
	v_pk_fma_f32 v[4:5], v[16:17], v[76:77], v[4:5] op_sel_hi:[1,0,1]
	v_pk_fma_f32 v[6:7], v[18:19], v[76:77], v[6:7] op_sel_hi:[1,0,1]
	v_pk_fma_f32 v[60:61], v[2:3], v[26:27], v[60:61]
	v_pk_mul_f32 v[62:63], v[4:5], v[24:25]
	v_pk_fma_f32 v[62:63], v[6:7], v[26:27], v[62:63]
	v_add_f32_e32 v108, v60, v61
	v_add_f32_e32 v124, v62, v63
	s_waitcnt lgkmcnt(0)
; DEV void scan_tile(const Params& p, int l, int tile, char* smem) {
;     ...
;       auto ldops = [&](ScanOps& o, int sl) {
;         const f32x4* b4 = (const f32x4*)(cb + sl * 384);
;         o.nkk0 = b4[cg * 2]; o.nkk1 = b4[cg * 2 + 1];
;         o.w0 = b4[16 + cg * 2]; o.w1 = b4[16 + cg * 2 + 1];
;         o.kka0 = b4[32 + cg * 2]; o.kka1 = b4[32 + cg * 2 + 1];
;         o.kd0 = b4[48 + cg * 2]; o.kd1 = b4[48 + cg * 2 + 1];
;         o.r0 = b4[64 + cg * 2]; o.r1 = b4[64 + cg * 2 + 1];
;         o.v = cb[sl * 384 + vo];
;       };
;       float ykeep = 0.f;
;       auto step = [&](const ScanOps& o, int sl) {
;         const f32x4 sA = S0 * o.nkk0 + S1 * o.nkk1;
;         const float sa = red8((sA[0] + sA[1]) + (sA[2] + sA[3]));
;         S0 = S0 * o.w0 + (o.kka0 * sa + o.kd0 * o.v);
;         S1 = S1 * o.w1 + (o.kka1 * sa + o.kd1 * o.v);
;         const f32x4 yA = S0 * o.r0 + S1 * o.r1;
;         const float y = red8((yA[0] + yA[1]) + (yA[2] + yA[3]));
;         ykeep = (cg == (sl & 7)) ? y : ykeep;
;       };
	ds_read_b128 v[8:11], v78 offset:18432
	ds_read_b128 v[12:15], v78 offset:18688
	ds_read_b128 v[16:19], v78 offset:18944
	ds_read_b128 v[20:23], v78 offset:19200
	ds_read_b128 v[24:27], v78 offset:19456
	ds_read2st64_b32 v[48:49], v79 offset0:77 offset1:83
	ds_read2st64_b32 v[52:53], v81 offset0:77 offset1:83
	v_pk_mul_f32 v[56:57], v[0:1], v[28:29]
	v_pk_mul_f32 v[58:59], v[4:5], v[28:29]
	v_pk_fma_f32 v[56:57], v[2:3], v[30:31], v[56:57]
	v_pk_fma_f32 v[58:59], v[6:7], v[30:31], v[58:59]
	v_add_f32_e32 v72, v56, v57
	v_add_f32_e32 v73, v58, v59
	v_pk_mul_f32 v[64:65], v[40:41], v[50:51] op_sel:[0,1] op_sel_hi:[1,1]
	v_pk_mul_f32 v[68:69], v[40:41], v[54:55] op_sel:[0,1] op_sel_hi:[1,1]
	v_add_f32_dpp v74, v73, v72 row_mirror row_mask:0xf bank_mask:0xf bound_ctrl:1
	v_pk_mul_f32 v[66:67], v[42:43], v[50:51] op_sel:[0,1] op_sel_hi:[1,1]
	v_pk_mul_f32 v[70:71], v[42:43], v[54:55] op_sel:[0,1] op_sel_hi:[1,1]
	v_add_f32_dpp v74, v74, v74 quad_perm:[1,0,3,2] row_mask:0xf bank_mask:0xf bound_ctrl:1
	v_pk_fma_f32 v[0:1], v[0:1], v[32:33], v[64:65]
	v_pk_fma_f32 v[4:5], v[4:5], v[32:33], v[68:69]
	v_add_f32_dpp v74, v74, v74 quad_perm:[2,3,0,1] row_mask:0xf bank_mask:0xf bound_ctrl:1
	v_pk_fma_f32 v[2:3], v[2:3], v[34:35], v[66:67]
	v_pk_fma_f32 v[6:7], v[6:7], v[34:35], v[70:71]
	v_add_f32_dpp v74, v74, v74 row_half_mirror row_mask:0xf bank_mask:0xf bound_ctrl:1
	v_pk_fma_f32 v[0:1], v[36:37], v[74:75], v[0:1] op_sel_hi:[1,0,1]
	v_pk_fma_f32 v[2:3], v[38:39], v[74:75], v[2:3] op_sel_hi:[1,0,1]
	v_mov_b32_dpp v76, v74 row_mirror row_mask:0xf bank_mask:0xf bound_ctrl:1
	v_pk_mul_f32 v[60:61], v[0:1], v[44:45]
	v_pk_fma_f32 v[4:5], v[36:37], v[76:77], v[4:5] op_sel_hi:[1,0,1]
	v_pk_fma_f32 v[6:7], v[38:39], v[76:77], v[6:7] op_sel_hi:[1,0,1]
	v_pk_fma_f32 v[60:61], v[2:3], v[46:47], v[60:61]
	v_pk_mul_f32 v[62:63], v[4:5], v[44:45]
	v_pk_fma_f32 v[62:63], v[6:7], v[46:47], v[62:63]
	v_add_f32_e32 v109, v60, v61
	v_add_f32_e32 v125, v62, v63
	s_waitcnt lgkmcnt(0)
	ds_read_b128 v[28:31], v78 offset:19968
	ds_read_b128 v[32:35], v78 offset:20224
	ds_read_b128 v[36:39], v78 offset:20480
	ds_read_b128 v[40:43], v78 offset:20736
	ds_read_b128 v[44:47], v78 offset:20992
	v_pk_mul_f32 v[56:57], v[0:1], v[8:9]
	v_pk_mul_f32 v[58:59], v[4:5], v[8:9]
	v_pk_fma_f32 v[56:57], v[2:3], v[10:11], v[56:57]
	v_pk_fma_f32 v[58:59], v[6:7], v[10:11], v[58:59]
	v_add_f32_e32 v72, v56, v57
	v_add_f32_e32 v73, v58, v59
	v_pk_mul_f32 v[64:65], v[20:21], v[48:49] op_sel_hi:[1,0]
	v_pk_mul_f32 v[68:69], v[20:21], v[52:53] op_sel_hi:[1,0]
	v_add_f32_dpp v74, v73, v72 row_mirror row_mask:0xf bank_mask:0xf bound_ctrl:1
	v_pk_mul_f32 v[66:67], v[22:23], v[48:49] op_sel_hi:[1,0]
	v_pk_mul_f32 v[70:71], v[22:23], v[52:53] op_sel_hi:[1,0]
	v_add_f32_dpp v74, v74, v74 quad_perm:[1,0,3,2] row_mask:0xf bank_mask:0xf bound_ctrl:1
	v_pk_fma_f32 v[0:1], v[0:1], v[12:13], v[64:65]
	v_pk_fma_f32 v[4:5], v[4:5], v[12:13], v[68:69]
	v_add_f32_dpp v74, v74, v74 quad_perm:[2,3,0,1] row_mask:0xf bank_mask:0xf bound_ctrl:1
	v_pk_fma_f32 v[2:3], v[2:3], v[14:15], v[66:67]
	v_pk_fma_f32 v[6:7], v[6:7], v[14:15], v[70:71]
	v_add_f32_dpp v74, v74, v74 row_half_mirror row_mask:0xf bank_mask:0xf bound_ctrl:1
	v_pk_fma_f32 v[0:1], v[16:17], v[74:75], v[0:1] op_sel_hi:[1,0,1]
	v_pk_fma_f32 v[2:3], v[18:19], v[74:75], v[2:3] op_sel_hi:[1,0,1]
	v_mov_b32_dpp v76, v74 row_mirror row_mask:0xf bank_mask:0xf bound_ctrl:1
	v_pk_mul_f32 v[60:61], v[0:1], v[24:25]
	v_pk_fma_f32 v[4:5], v[16:17], v[76:77], v[4:5] op_sel_hi:[1,0,1]
	v_pk_fma_f32 v[6:7], v[18:19], v[76:77], v[6:7] op_sel_hi:[1,0,1]
	v_pk_fma_f32 v[60:61], v[2:3], v[26:27], v[60:61]
	v_pk_mul_f32 v[62:63], v[4:5], v[24:25]
	v_pk_fma_f32 v[62:63], v[6:7], v[26:27], v[62:63]
	v_add_f32_e32 v110, v60, v61
	v_add_f32_e32 v126, v62, v63
	s_waitcnt lgkmcnt(0)
	ds_read_b128 v[8:11], v78 offset:21504
	ds_read_b128 v[12:15], v78 offset:21760
	ds_read_b128 v[16:19], v78 offset:22016
	ds_read_b128 v[20:23], v78 offset:22272
	ds_read_b128 v[24:27], v78 offset:22528
	ds_read2st64_b32 v[50:51], v79 offset0:89 offset1:95
	ds_read2st64_b32 v[54:55], v81 offset0:89 offset1:95
	v_pk_mul_f32 v[56:57], v[0:1], v[28:29]
	v_pk_mul_f32 v[58:59], v[4:5], v[28:29]
	v_pk_fma_f32 v[56:57], v[2:3], v[30:31], v[56:57]
	v_pk_fma_f32 v[58:59], v[6:7], v[30:31], v[58:59]
	v_add_f32_e32 v72, v56, v57
	v_add_f32_e32 v73, v58, v59
	v_pk_mul_f32 v[64:65], v[40:41], v[48:49] op_sel:[0,1] op_sel_hi:[1,1]
	v_pk_mul_f32 v[68:69], v[40:41], v[52:53] op_sel:[0,1] op_sel_hi:[1,1]
	v_add_f32_dpp v74, v73, v72 row_mirror row_mask:0xf bank_mask:0xf bound_ctrl:1
	v_pk_mul_f32 v[66:67], v[42:43], v[48:49] op_sel:[0,1] op_sel_hi:[1,1]
	v_pk_mul_f32 v[70:71], v[42:43], v[52:53] op_sel:[0,1] op_sel_hi:[1,1]
	v_add_f32_dpp v74, v74, v74 quad_perm:[1,0,3,2] row_mask:0xf bank_mask:0xf bound_ctrl:1
	v_pk_fma_f32 v[0:1], v[0:1], v[32:33], v[64:65]
	v_pk_fma_f32 v[4:5], v[4:5], v[32:33], v[68:69]
	v_add_f32_dpp v74, v74, v74 quad_perm:[2,3,0,1] row_mask:0xf bank_mask:0xf bound_ctrl:1
	v_pk_fma_f32 v[2:3], v[2:3], v[34:35], v[66:67]
	v_pk_fma_f32 v[6:7], v[6:7], v[34:35], v[70:71]
	v_add_f32_dpp v74, v74, v74 row_half_mirror row_mask:0xf bank_mask:0xf bound_ctrl:1
	v_pk_fma_f32 v[0:1], v[36:37], v[74:75], v[0:1] op_sel_hi:[1,0,1]
	v_pk_fma_f32 v[2:3], v[38:39], v[74:75], v[2:3] op_sel_hi:[1,0,1]
	v_mov_b32_dpp v76, v74 row_mirror row_mask:0xf bank_mask:0xf bound_ctrl:1
	v_pk_mul_f32 v[60:61], v[0:1], v[44:45]
	v_pk_fma_f32 v[4:5], v[36:37], v[76:77], v[4:5] op_sel_hi:[1,0,1]
	v_pk_fma_f32 v[6:7], v[38:39], v[76:77], v[6:7] op_sel_hi:[1,0,1]
	v_pk_fma_f32 v[60:61], v[2:3], v[46:47], v[60:61]
	v_pk_mul_f32 v[62:63], v[4:5], v[44:45]
	v_pk_fma_f32 v[62:63], v[6:7], v[46:47], v[62:63]
	v_add_f32_e32 v111, v60, v61
	v_add_f32_e32 v127, v62, v63
	s_waitcnt lgkmcnt(0)
; DEV void scan_tile(const Params& p, int l, int tile, char* smem) {
;     ...
;       auto step = [&](const ScanOps& o, int sl) {
;         const f32x4 sA = S0 * o.nkk0 + S1 * o.nkk1;
;         const float sa = red8((sA[0] + sA[1]) + (sA[2] + sA[3]));
;         S0 = S0 * o.w0 + (o.kka0 * sa + o.kd0 * o.v);
;         S1 = S1 * o.w1 + (o.kka1 * sa + o.kd1 * o.v);
;         const f32x4 yA = S0 * o.r0 + S1 * o.r1;
;         const float y = red8((yA[0] + yA[1]) + (yA[2] + yA[3]));
;         ykeep = (cg == (sl & 7)) ? y : ykeep;
;       };
;       ScanOps oa, ob;
;       ldops(oa, 0);
; #pragma unroll
;       for (int s8 = 0; s8 < 32; s8 += 8) {
; #pragma unroll
;         for (int q = 0; q < 8; q += 2) {
;           ldops(ob, s8 + q + 1);
;           step(oa, s8 + q);
;           ldops(oa, (s8 + q + 2) & 31);
;           step(ob, s8 + q + 1);
;         }
;         yw[s8 * 32] = ykeep;
	ds_read_b128 v[28:31], v78 offset:23040
	ds_read_b128 v[32:35], v78 offset:23296
	ds_read_b128 v[36:39], v78 offset:23552
	ds_read_b128 v[40:43], v78 offset:23808
	ds_read_b128 v[44:47], v78 offset:24064
	v_pk_mul_f32 v[56:57], v[0:1], v[8:9]
	v_pk_mul_f32 v[58:59], v[4:5], v[8:9]
	v_pk_fma_f32 v[56:57], v[2:3], v[10:11], v[56:57]
	v_pk_fma_f32 v[58:59], v[6:7], v[10:11], v[58:59]
	v_add_f32_e32 v72, v56, v57
	v_add_f32_e32 v73, v58, v59
	v_pk_mul_f32 v[64:65], v[20:21], v[50:51] op_sel_hi:[1,0]
	v_pk_mul_f32 v[68:69], v[20:21], v[54:55] op_sel_hi:[1,0]
	v_add_f32_dpp v74, v73, v72 row_mirror row_mask:0xf bank_mask:0xf bound_ctrl:1
	v_pk_mul_f32 v[66:67], v[22:23], v[50:51] op_sel_hi:[1,0]
	v_pk_mul_f32 v[70:71], v[22:23], v[54:55] op_sel_hi:[1,0]
	v_add_f32_dpp v74, v74, v74 quad_perm:[1,0,3,2] row_mask:0xf bank_mask:0xf bound_ctrl:1
	v_pk_fma_f32 v[0:1], v[0:1], v[12:13], v[64:65]
	v_pk_fma_f32 v[4:5], v[4:5], v[12:13], v[68:69]
	v_add_f32_dpp v74, v74, v74 quad_perm:[2,3,0,1] row_mask:0xf bank_mask:0xf bound_ctrl:1
	v_pk_fma_f32 v[2:3], v[2:3], v[14:15], v[66:67]
	v_pk_fma_f32 v[6:7], v[6:7], v[14:15], v[70:71]
	v_add_f32_dpp v74, v74, v74 row_half_mirror row_mask:0xf bank_mask:0xf bound_ctrl:1
	v_pk_fma_f32 v[0:1], v[16:17], v[74:75], v[0:1] op_sel_hi:[1,0,1]
	v_pk_fma_f32 v[2:3], v[18:19], v[74:75], v[2:3] op_sel_hi:[1,0,1]
	v_mov_b32_dpp v76, v74 row_mirror row_mask:0xf bank_mask:0xf bound_ctrl:1
	v_pk_mul_f32 v[60:61], v[0:1], v[24:25]
	v_pk_fma_f32 v[4:5], v[16:17], v[76:77], v[4:5] op_sel_hi:[1,0,1]
	v_pk_fma_f32 v[6:7], v[18:19], v[76:77], v[6:7] op_sel_hi:[1,0,1]
	v_pk_fma_f32 v[60:61], v[2:3], v[26:27], v[60:61]
	v_pk_mul_f32 v[62:63], v[4:5], v[24:25]
	v_pk_fma_f32 v[62:63], v[6:7], v[26:27], v[62:63]
	v_add_f32_e32 v112, v60, v61
	v_add_f32_e32 v94, v62, v63
	s_waitcnt lgkmcnt(0)
	ds_read_b128 v[8:11], v78 offset:24576
	ds_read_b128 v[12:15], v78 offset:24832
	ds_read_b128 v[16:19], v78 offset:25088
	ds_read_b128 v[20:23], v78 offset:25344
	ds_read_b128 v[24:27], v78 offset:25600
	ds_read2st64_b32 v[48:49], v79 offset0:101 offset1:107
	ds_read2st64_b32 v[52:53], v81 offset0:101 offset1:107
	v_pk_mul_f32 v[56:57], v[0:1], v[28:29]
	v_pk_mul_f32 v[58:59], v[4:5], v[28:29]
	v_pk_fma_f32 v[56:57], v[2:3], v[30:31], v[56:57]
	v_pk_fma_f32 v[58:59], v[6:7], v[30:31], v[58:59]
	v_add_f32_e32 v72, v56, v57
	v_add_f32_e32 v73, v58, v59
	v_pk_mul_f32 v[64:65], v[40:41], v[50:51] op_sel:[0,1] op_sel_hi:[1,1]
	v_pk_mul_f32 v[68:69], v[40:41], v[54:55] op_sel:[0,1] op_sel_hi:[1,1]
	v_add_f32_dpp v74, v73, v72 row_mirror row_mask:0xf bank_mask:0xf bound_ctrl:1
	v_pk_mul_f32 v[66:67], v[42:43], v[50:51] op_sel:[0,1] op_sel_hi:[1,1]
	v_pk_mul_f32 v[70:71], v[42:43], v[54:55] op_sel:[0,1] op_sel_hi:[1,1]
	v_add_f32_dpp v74, v74, v74 quad_perm:[1,0,3,2] row_mask:0xf bank_mask:0xf bound_ctrl:1
	v_pk_fma_f32 v[0:1], v[0:1], v[32:33], v[64:65]
	v_pk_fma_f32 v[4:5], v[4:5], v[32:33], v[68:69]
	v_add_f32_dpp v74, v74, v74 quad_perm:[2,3,0,1] row_mask:0xf bank_mask:0xf bound_ctrl:1
	v_pk_fma_f32 v[2:3], v[2:3], v[34:35], v[66:67]
	v_pk_fma_f32 v[6:7], v[6:7], v[34:35], v[70:71]
	v_add_f32_dpp v74, v74, v74 row_half_mirror row_mask:0xf bank_mask:0xf bound_ctrl:1
	v_pk_fma_f32 v[0:1], v[36:37], v[74:75], v[0:1] op_sel_hi:[1,0,1]
	v_pk_fma_f32 v[2:3], v[38:39], v[74:75], v[2:3] op_sel_hi:[1,0,1]
	v_mov_b32_dpp v76, v74 row_mirror row_mask:0xf bank_mask:0xf bound_ctrl:1
	v_pk_mul_f32 v[60:61], v[0:1], v[44:45]
	v_pk_fma_f32 v[4:5], v[36:37], v[76:77], v[4:5] op_sel_hi:[1,0,1]
	v_pk_fma_f32 v[6:7], v[38:39], v[76:77], v[6:7] op_sel_hi:[1,0,1]
	v_pk_fma_f32 v[60:61], v[2:3], v[46:47], v[60:61]
	v_pk_mul_f32 v[62:63], v[4:5], v[44:45]
	v_pk_fma_f32 v[62:63], v[6:7], v[46:47], v[62:63]
	v_add_f32_e32 v113, v60, v61
	v_add_f32_e32 v95, v62, v63
	v_add_f32_dpp v84, v114, v98 row_mirror row_mask:0xf bank_mask:0x3 bound_ctrl:1
	v_add_f32_dpp v84, v122, v106 row_mirror row_mask:0xf bank_mask:0xc bound_ctrl:1
	v_add_f32_dpp v85, v115, v99 row_mirror row_mask:0xf bank_mask:0x3 bound_ctrl:1
	v_add_f32_dpp v85, v123, v107 row_mirror row_mask:0xf bank_mask:0xc bound_ctrl:1
	v_add_f32_dpp v86, v116, v100 row_mirror row_mask:0xf bank_mask:0x3 bound_ctrl:1
	v_add_f32_dpp v86, v124, v108 row_mirror row_mask:0xf bank_mask:0xc bound_ctrl:1
	v_add_f32_dpp v87, v117, v101 row_mirror row_mask:0xf bank_mask:0x3 bound_ctrl:1
	v_add_f32_dpp v87, v125, v109 row_mirror row_mask:0xf bank_mask:0xc bound_ctrl:1
	v_add_f32_dpp v88, v118, v102 row_mirror row_mask:0xf bank_mask:0x3 bound_ctrl:1
	v_add_f32_dpp v88, v126, v110 row_mirror row_mask:0xf bank_mask:0xc bound_ctrl:1
	v_add_f32_dpp v89, v119, v103 row_mirror row_mask:0xf bank_mask:0x3 bound_ctrl:1
	v_add_f32_dpp v89, v127, v111 row_mirror row_mask:0xf bank_mask:0xc bound_ctrl:1
	v_add_f32_dpp v90, v120, v104 row_mirror row_mask:0xf bank_mask:0x3 bound_ctrl:1
	v_add_f32_dpp v90, v94, v112 row_mirror row_mask:0xf bank_mask:0xc bound_ctrl:1
	v_add_f32_dpp v91, v121, v105 row_mirror row_mask:0xf bank_mask:0x3 bound_ctrl:1
	v_add_f32_dpp v91, v95, v113 row_mirror row_mask:0xf bank_mask:0xc bound_ctrl:1
	v_add_f32_dpp v114, v98, v114 row_mirror row_mask:0xf bank_mask:0x3 bound_ctrl:1
	v_add_f32_dpp v114, v106, v122 row_mirror row_mask:0xf bank_mask:0xc bound_ctrl:1
	v_add_f32_dpp v115, v99, v115 row_mirror row_mask:0xf bank_mask:0x3 bound_ctrl:1
	v_add_f32_dpp v115, v107, v123 row_mirror row_mask:0xf bank_mask:0xc bound_ctrl:1
	v_add_f32_dpp v116, v100, v116 row_mirror row_mask:0xf bank_mask:0x3 bound_ctrl:1
	v_add_f32_dpp v116, v108, v124 row_mirror row_mask:0xf bank_mask:0xc bound_ctrl:1
; DEV void scan_tile(const Params& p, int l, int tile, char* smem) {
;     ...
;       auto ldops = [&](ScanOps& o, int sl) {
;         const f32x4* b4 = (const f32x4*)(cb + sl * 384);
;         o.nkk0 = b4[cg * 2]; o.nkk1 = b4[cg * 2 + 1];
;         o.w0 = b4[16 + cg * 2]; o.w1 = b4[16 + cg * 2 + 1];
;         o.kka0 = b4[32 + cg * 2]; o.kka1 = b4[32 + cg * 2 + 1];
;         o.kd0 = b4[48 + cg * 2]; o.kd1 = b4[48 + cg * 2 + 1];
;         o.r0 = b4[64 + cg * 2]; o.r1 = b4[64 + cg * 2 + 1];
;         o.v = cb[sl * 384 + vo];
;       };
;       float ykeep = 0.f;
;       auto step = [&](const ScanOps& o, int sl) {
;         const f32x4 sA = S0 * o.nkk0 + S1 * o.nkk1;
;         const float sa = red8((sA[0] + sA[1]) + (sA[2] + sA[3]));
;         S0 = S0 * o.w0 + (o.kka0 * sa + o.kd0 * o.v);
;         S1 = S1 * o.w1 + (o.kka1 * sa + o.kd1 * o.v);
;         const f32x4 yA = S0 * o.r0 + S1 * o.r1;
;         const float y = red8((yA[0] + yA[1]) + (yA[2] + yA[3]));
;         ykeep = (cg == (sl & 7)) ? y : ykeep;
;       };
;       ScanOps oa, ob;
;       ldops(oa, 0);
; #pragma unroll
;       for (int s8 = 0; s8 < 32; s8 += 8) {
; #pragma unroll
;         for (int q = 0; q < 8; q += 2) {
;           ldops(ob, s8 + q + 1);
;           step(oa, s8 + q);
;           ldops(oa, (s8 + q + 2) & 31);
;           step(ob, s8 + q + 1);
;         }
;         yw[s8 * 32] = ykeep;
	v_add_f32_dpp v117, v101, v117 row_mirror row_mask:0xf bank_mask:0x3 bound_ctrl:1
	v_add_f32_dpp v117, v109, v125 row_mirror row_mask:0xf bank_mask:0xc bound_ctrl:1
	v_add_f32_dpp v118, v102, v118 row_mirror row_mask:0xf bank_mask:0x3 bound_ctrl:1
	v_add_f32_dpp v118, v110, v126 row_mirror row_mask:0xf bank_mask:0xc bound_ctrl:1
	v_add_f32_dpp v119, v103, v119 row_mirror row_mask:0xf bank_mask:0x3 bound_ctrl:1
	v_add_f32_dpp v119, v111, v127 row_mirror row_mask:0xf bank_mask:0xc bound_ctrl:1
	v_add_f32_dpp v120, v104, v120 row_mirror row_mask:0xf bank_mask:0x3 bound_ctrl:1
	v_add_f32_dpp v120, v112, v94 row_mirror row_mask:0xf bank_mask:0xc bound_ctrl:1
	v_add_f32_dpp v121, v105, v121 row_mirror row_mask:0xf bank_mask:0x3 bound_ctrl:1
	v_add_f32_dpp v121, v113, v95 row_mirror row_mask:0xf bank_mask:0xc bound_ctrl:1
	v_add_f32_dpp v84, v84, v84 row_half_mirror row_mask:0xf bank_mask:0x5 bound_ctrl:1
	v_add_f32_dpp v84, v88, v88 row_half_mirror row_mask:0xf bank_mask:0xa bound_ctrl:1
	v_add_f32_dpp v85, v85, v85 row_half_mirror row_mask:0xf bank_mask:0x5 bound_ctrl:1
	v_add_f32_dpp v85, v89, v89 row_half_mirror row_mask:0xf bank_mask:0xa bound_ctrl:1
	v_add_f32_dpp v86, v86, v86 row_half_mirror row_mask:0xf bank_mask:0x5 bound_ctrl:1
	v_add_f32_dpp v86, v90, v90 row_half_mirror row_mask:0xf bank_mask:0xa bound_ctrl:1
	v_add_f32_dpp v87, v87, v87 row_half_mirror row_mask:0xf bank_mask:0x5 bound_ctrl:1
	v_add_f32_dpp v87, v91, v91 row_half_mirror row_mask:0xf bank_mask:0xa bound_ctrl:1
	v_add_f32_dpp v84, v84, v84 quad_perm:[2,3,0,1] row_mask:0xf bank_mask:0xf bound_ctrl:1
	v_add_f32_dpp v85, v85, v85 quad_perm:[2,3,0,1] row_mask:0xf bank_mask:0xf bound_ctrl:1
	v_add_f32_dpp v86, v86, v86 quad_perm:[2,3,0,1] row_mask:0xf bank_mask:0xf bound_ctrl:1
	v_add_f32_dpp v87, v87, v87 quad_perm:[2,3,0,1] row_mask:0xf bank_mask:0xf bound_ctrl:1
	v_cndmask_b32_e64 v88, v86, v84, s[62:63]
	v_cndmask_b32_e64 v89, v87, v85, s[62:63]
	s_nop 0
	v_add_f32_dpp v88, v88, v88 quad_perm:[1,0,3,2] row_mask:0xf bank_mask:0xf bound_ctrl:1
	v_add_f32_dpp v89, v89, v89 quad_perm:[1,0,3,2] row_mask:0xf bank_mask:0xf bound_ctrl:1
	v_cndmask_b32_e64 v90, v89, v88, s[64:65]
	ds_write_b32 v80, v90 offset:0
	v_add_f32_dpp v114, v114, v114 row_half_mirror row_mask:0xf bank_mask:0x5 bound_ctrl:1
	v_add_f32_dpp v114, v118, v118 row_half_mirror row_mask:0xf bank_mask:0xa bound_ctrl:1
	v_add_f32_dpp v115, v115, v115 row_half_mirror row_mask:0xf bank_mask:0x5 bound_ctrl:1
	v_add_f32_dpp v115, v119, v119 row_half_mirror row_mask:0xf bank_mask:0xa bound_ctrl:1
	v_add_f32_dpp v116, v116, v116 row_half_mirror row_mask:0xf bank_mask:0x5 bound_ctrl:1
	v_add_f32_dpp v116, v120, v120 row_half_mirror row_mask:0xf bank_mask:0xa bound_ctrl:1
	v_add_f32_dpp v117, v117, v117 row_half_mirror row_mask:0xf bank_mask:0x5 bound_ctrl:1
	v_add_f32_dpp v117, v121, v121 row_half_mirror row_mask:0xf bank_mask:0xa bound_ctrl:1
	v_add_f32_dpp v114, v114, v114 quad_perm:[2,3,0,1] row_mask:0xf bank_mask:0xf bound_ctrl:1
	v_add_f32_dpp v115, v115, v115 quad_perm:[2,3,0,1] row_mask:0xf bank_mask:0xf bound_ctrl:1
	v_add_f32_dpp v116, v116, v116 quad_perm:[2,3,0,1] row_mask:0xf bank_mask:0xf bound_ctrl:1
	v_add_f32_dpp v117, v117, v117 quad_perm:[2,3,0,1] row_mask:0xf bank_mask:0xf bound_ctrl:1
	v_cndmask_b32_e64 v118, v116, v114, s[62:63]
	v_cndmask_b32_e64 v119, v117, v115, s[62:63]
	s_nop 0
	v_add_f32_dpp v118, v118, v118 quad_perm:[1,0,3,2] row_mask:0xf bank_mask:0xf bound_ctrl:1
	v_add_f32_dpp v119, v119, v119 quad_perm:[1,0,3,2] row_mask:0xf bank_mask:0xf bound_ctrl:1
	v_cndmask_b32_e64 v120, v119, v118, s[64:65]
	ds_write_b32 v82, v120 offset:0
	s_waitcnt lgkmcnt(2)
	ds_read_b128 v[28:31], v78 offset:26112
	ds_read_b128 v[32:35], v78 offset:26368
	ds_read_b128 v[36:39], v78 offset:26624
	ds_read_b128 v[40:43], v78 offset:26880
	ds_read_b128 v[44:47], v78 offset:27136
	v_pk_mul_f32 v[56:57], v[0:1], v[8:9]
	v_pk_mul_f32 v[58:59], v[4:5], v[8:9]
	v_pk_fma_f32 v[56:57], v[2:3], v[10:11], v[56:57]
	v_pk_fma_f32 v[58:59], v[6:7], v[10:11], v[58:59]
	v_add_f32_e32 v72, v56, v57
	v_add_f32_e32 v73, v58, v59
	v_pk_mul_f32 v[64:65], v[20:21], v[48:49] op_sel_hi:[1,0]
	v_pk_mul_f32 v[68:69], v[20:21], v[52:53] op_sel_hi:[1,0]
	v_add_f32_dpp v74, v73, v72 row_mirror row_mask:0xf bank_mask:0xf bound_ctrl:1
	v_pk_mul_f32 v[66:67], v[22:23], v[48:49] op_sel_hi:[1,0]
	v_pk_mul_f32 v[70:71], v[22:23], v[52:53] op_sel_hi:[1,0]
	v_add_f32_dpp v74, v74, v74 quad_perm:[1,0,3,2] row_mask:0xf bank_mask:0xf bound_ctrl:1
	v_pk_fma_f32 v[0:1], v[0:1], v[12:13], v[64:65]
	v_pk_fma_f32 v[4:5], v[4:5], v[12:13], v[68:69]
	v_add_f32_dpp v74, v74, v74 quad_perm:[2,3,0,1] row_mask:0xf bank_mask:0xf bound_ctrl:1
	v_pk_fma_f32 v[2:3], v[2:3], v[14:15], v[66:67]
	v_pk_fma_f32 v[6:7], v[6:7], v[14:15], v[70:71]
	v_add_f32_dpp v74, v74, v74 row_half_mirror row_mask:0xf bank_mask:0xf bound_ctrl:1
	v_pk_fma_f32 v[0:1], v[16:17], v[74:75], v[0:1] op_sel_hi:[1,0,1]
	v_pk_fma_f32 v[2:3], v[18:19], v[74:75], v[2:3] op_sel_hi:[1,0,1]
	v_mov_b32_dpp v76, v74 row_mirror row_mask:0xf bank_mask:0xf bound_ctrl:1
	v_pk_mul_f32 v[60:61], v[0:1], v[24:25]
	v_pk_fma_f32 v[4:5], v[16:17], v[76:77], v[4:5] op_sel_hi:[1,0,1]
	v_pk_fma_f32 v[6:7], v[18:19], v[76:77], v[6:7] op_sel_hi:[1,0,1]
	v_pk_fma_f32 v[60:61], v[2:3], v[26:27], v[60:61]
	v_pk_mul_f32 v[62:63], v[4:5], v[24:25]
	v_pk_fma_f32 v[62:63], v[6:7], v[26:27], v[62:63]
	v_add_f32_e32 v98, v60, v61
	v_add_f32_e32 v114, v62, v63
	s_waitcnt lgkmcnt(0)
; DEV void scan_tile(const Params& p, int l, int tile, char* smem) {
;     ...
;       auto ldops = [&](ScanOps& o, int sl) {
;         const f32x4* b4 = (const f32x4*)(cb + sl * 384);
;         o.nkk0 = b4[cg * 2]; o.nkk1 = b4[cg * 2 + 1];
;         o.w0 = b4[16 + cg * 2]; o.w1 = b4[16 + cg * 2 + 1];
;         o.kka0 = b4[32 + cg * 2]; o.kka1 = b4[32 + cg * 2 + 1];
;         o.kd0 = b4[48 + cg * 2]; o.kd1 = b4[48 + cg * 2 + 1];
;         o.r0 = b4[64 + cg * 2]; o.r1 = b4[64 + cg * 2 + 1];
;         o.v = cb[sl * 384 + vo];
;       };
;       float ykeep = 0.f;
;       auto step = [&](const ScanOps& o, int sl) {
;         const f32x4 sA = S0 * o.nkk0 + S1 * o.nkk1;
;         const float sa = red8((sA[0] + sA[1]) + (sA[2] + sA[3]));
;         S0 = S0 * o.w0 + (o.kka0 * sa + o.kd0 * o.v);
;         S1 = S1 * o.w1 + (o.kka1 * sa + o.kd1 * o.v);
;         const f32x4 yA = S0 * o.r0 + S1 * o.r1;
;         const float y = red8((yA[0] + yA[1]) + (yA[2] + yA[3]));
;         ykeep = (cg == (sl & 7)) ? y : ykeep;
;       };
	ds_read_b128 v[8:11], v78 offset:27648
	ds_read_b128 v[12:15], v78 offset:27904
	ds_read_b128 v[16:19], v78 offset:28160
	ds_read_b128 v[20:23], v78 offset:28416
	ds_read_b128 v[24:27], v78 offset:28672
	ds_read2st64_b32 v[50:51], v79 offset0:113 offset1:119
	ds_read2st64_b32 v[54:55], v81 offset0:113 offset1:119
	v_pk_mul_f32 v[56:57], v[0:1], v[28:29]
	v_pk_mul_f32 v[58:59], v[4:5], v[28:29]
	v_pk_fma_f32 v[56:57], v[2:3], v[30:31], v[56:57]
	v_pk_fma_f32 v[58:59], v[6:7], v[30:31], v[58:59]
	v_add_f32_e32 v72, v56, v57
	v_add_f32_e32 v73, v58, v59
	v_pk_mul_f32 v[64:65], v[40:41], v[48:49] op_sel:[0,1] op_sel_hi:[1,1]
	v_pk_mul_f32 v[68:69], v[40:41], v[52:53] op_sel:[0,1] op_sel_hi:[1,1]
	v_add_f32_dpp v74, v73, v72 row_mirror row_mask:0xf bank_mask:0xf bound_ctrl:1
	v_pk_mul_f32 v[66:67], v[42:43], v[48:49] op_sel:[0,1] op_sel_hi:[1,1]
	v_pk_mul_f32 v[70:71], v[42:43], v[52:53] op_sel:[0,1] op_sel_hi:[1,1]
	v_add_f32_dpp v74, v74, v74 quad_perm:[1,0,3,2] row_mask:0xf bank_mask:0xf bound_ctrl:1
	v_pk_fma_f32 v[0:1], v[0:1], v[32:33], v[64:65]
	v_pk_fma_f32 v[4:5], v[4:5], v[32:33], v[68:69]
	v_add_f32_dpp v74, v74, v74 quad_perm:[2,3,0,1] row_mask:0xf bank_mask:0xf bound_ctrl:1
	v_pk_fma_f32 v[2:3], v[2:3], v[34:35], v[66:67]
	v_pk_fma_f32 v[6:7], v[6:7], v[34:35], v[70:71]
	v_add_f32_dpp v74, v74, v74 row_half_mirror row_mask:0xf bank_mask:0xf bound_ctrl:1
	v_pk_fma_f32 v[0:1], v[36:37], v[74:75], v[0:1] op_sel_hi:[1,0,1]
	v_pk_fma_f32 v[2:3], v[38:39], v[74:75], v[2:3] op_sel_hi:[1,0,1]
	v_mov_b32_dpp v76, v74 row_mirror row_mask:0xf bank_mask:0xf bound_ctrl:1
	v_pk_mul_f32 v[60:61], v[0:1], v[44:45]
	v_pk_fma_f32 v[4:5], v[36:37], v[76:77], v[4:5] op_sel_hi:[1,0,1]
	v_pk_fma_f32 v[6:7], v[38:39], v[76:77], v[6:7] op_sel_hi:[1,0,1]
	v_pk_fma_f32 v[60:61], v[2:3], v[46:47], v[60:61]
	v_pk_mul_f32 v[62:63], v[4:5], v[44:45]
	v_pk_fma_f32 v[62:63], v[6:7], v[46:47], v[62:63]
	v_add_f32_e32 v99, v60, v61
	v_add_f32_e32 v115, v62, v63
	s_waitcnt lgkmcnt(0)
	ds_read_b128 v[28:31], v78 offset:29184
	ds_read_b128 v[32:35], v78 offset:29440
	ds_read_b128 v[36:39], v78 offset:29696
	ds_read_b128 v[40:43], v78 offset:29952
	ds_read_b128 v[44:47], v78 offset:30208
	v_pk_mul_f32 v[56:57], v[0:1], v[8:9]
	v_pk_mul_f32 v[58:59], v[4:5], v[8:9]
	v_pk_fma_f32 v[56:57], v[2:3], v[10:11], v[56:57]
	v_pk_fma_f32 v[58:59], v[6:7], v[10:11], v[58:59]
	v_add_f32_e32 v72, v56, v57
	v_add_f32_e32 v73, v58, v59
	v_pk_mul_f32 v[64:65], v[20:21], v[50:51] op_sel_hi:[1,0]
	v_pk_mul_f32 v[68:69], v[20:21], v[54:55] op_sel_hi:[1,0]
	v_add_f32_dpp v74, v73, v72 row_mirror row_mask:0xf bank_mask:0xf bound_ctrl:1
	v_pk_mul_f32 v[66:67], v[22:23], v[50:51] op_sel_hi:[1,0]
	v_pk_mul_f32 v[70:71], v[22:23], v[54:55] op_sel_hi:[1,0]
	v_add_f32_dpp v74, v74, v74 quad_perm:[1,0,3,2] row_mask:0xf bank_mask:0xf bound_ctrl:1
	v_pk_fma_f32 v[0:1], v[0:1], v[12:13], v[64:65]
	v_pk_fma_f32 v[4:5], v[4:5], v[12:13], v[68:69]
	v_add_f32_dpp v74, v74, v74 quad_perm:[2,3,0,1] row_mask:0xf bank_mask:0xf bound_ctrl:1
	v_pk_fma_f32 v[2:3], v[2:3], v[14:15], v[66:67]
	v_pk_fma_f32 v[6:7], v[6:7], v[14:15], v[70:71]
	v_add_f32_dpp v74, v74, v74 row_half_mirror row_mask:0xf bank_mask:0xf bound_ctrl:1
	v_pk_fma_f32 v[0:1], v[16:17], v[74:75], v[0:1] op_sel_hi:[1,0,1]
	v_pk_fma_f32 v[2:3], v[18:19], v[74:75], v[2:3] op_sel_hi:[1,0,1]
	v_mov_b32_dpp v76, v74 row_mirror row_mask:0xf bank_mask:0xf bound_ctrl:1
	v_pk_mul_f32 v[60:61], v[0:1], v[24:25]
	v_pk_fma_f32 v[4:5], v[16:17], v[76:77], v[4:5] op_sel_hi:[1,0,1]
	v_pk_fma_f32 v[6:7], v[18:19], v[76:77], v[6:7] op_sel_hi:[1,0,1]
	v_pk_fma_f32 v[60:61], v[2:3], v[26:27], v[60:61]
	v_pk_mul_f32 v[62:63], v[4:5], v[24:25]
	v_pk_fma_f32 v[62:63], v[6:7], v[26:27], v[62:63]
	v_add_f32_e32 v100, v60, v61
	v_add_f32_e32 v116, v62, v63
	s_waitcnt lgkmcnt(0)
	ds_read_b128 v[8:11], v78 offset:30720
	ds_read_b128 v[12:15], v78 offset:30976
	ds_read_b128 v[16:19], v78 offset:31232
	ds_read_b128 v[20:23], v78 offset:31488
	ds_read_b128 v[24:27], v78 offset:31744
	ds_read2st64_b32 v[48:49], v79 offset0:125 offset1:131
	ds_read2st64_b32 v[52:53], v81 offset0:125 offset1:131
	v_pk_mul_f32 v[56:57], v[0:1], v[28:29]
	v_pk_mul_f32 v[58:59], v[4:5], v[28:29]
	v_pk_fma_f32 v[56:57], v[2:3], v[30:31], v[56:57]
	v_pk_fma_f32 v[58:59], v[6:7], v[30:31], v[58:59]
	v_add_f32_e32 v72, v56, v57
	v_add_f32_e32 v73, v58, v59
	v_pk_mul_f32 v[64:65], v[40:41], v[50:51] op_sel:[0,1] op_sel_hi:[1,1]
	v_pk_mul_f32 v[68:69], v[40:41], v[54:55] op_sel:[0,1] op_sel_hi:[1,1]
	v_add_f32_dpp v74, v73, v72 row_mirror row_mask:0xf bank_mask:0xf bound_ctrl:1
	v_pk_mul_f32 v[66:67], v[42:43], v[50:51] op_sel:[0,1] op_sel_hi:[1,1]
	v_pk_mul_f32 v[70:71], v[42:43], v[54:55] op_sel:[0,1] op_sel_hi:[1,1]
	v_add_f32_dpp v74, v74, v74 quad_perm:[1,0,3,2] row_mask:0xf bank_mask:0xf bound_ctrl:1
	v_pk_fma_f32 v[0:1], v[0:1], v[32:33], v[64:65]
	v_pk_fma_f32 v[4:5], v[4:5], v[32:33], v[68:69]
	v_add_f32_dpp v74, v74, v74 quad_perm:[2,3,0,1] row_mask:0xf bank_mask:0xf bound_ctrl:1
	v_pk_fma_f32 v[2:3], v[2:3], v[34:35], v[66:67]
	v_pk_fma_f32 v[6:7], v[6:7], v[34:35], v[70:71]
	v_add_f32_dpp v74, v74, v74 row_half_mirror row_mask:0xf bank_mask:0xf bound_ctrl:1
	v_pk_fma_f32 v[0:1], v[36:37], v[74:75], v[0:1] op_sel_hi:[1,0,1]
	v_pk_fma_f32 v[2:3], v[38:39], v[74:75], v[2:3] op_sel_hi:[1,0,1]
	v_mov_b32_dpp v76, v74 row_mirror row_mask:0xf bank_mask:0xf bound_ctrl:1
	v_pk_mul_f32 v[60:61], v[0:1], v[44:45]
	v_pk_fma_f32 v[4:5], v[36:37], v[76:77], v[4:5] op_sel_hi:[1,0,1]
	v_pk_fma_f32 v[6:7], v[38:39], v[76:77], v[6:7] op_sel_hi:[1,0,1]
	v_pk_fma_f32 v[60:61], v[2:3], v[46:47], v[60:61]
	v_pk_mul_f32 v[62:63], v[4:5], v[44:45]
	v_pk_fma_f32 v[62:63], v[6:7], v[46:47], v[62:63]
	v_add_f32_e32 v101, v60, v61
	v_add_f32_e32 v117, v62, v63
	s_waitcnt lgkmcnt(0)
; DEV void scan_tile(const Params& p, int l, int tile, char* smem) {
;     ...
;       auto ldops = [&](ScanOps& o, int sl) {
;         const f32x4* b4 = (const f32x4*)(cb + sl * 384);
;         o.nkk0 = b4[cg * 2]; o.nkk1 = b4[cg * 2 + 1];
;         o.w0 = b4[16 + cg * 2]; o.w1 = b4[16 + cg * 2 + 1];
;         o.kka0 = b4[32 + cg * 2]; o.kka1 = b4[32 + cg * 2 + 1];
;         o.kd0 = b4[48 + cg * 2]; o.kd1 = b4[48 + cg * 2 + 1];
;         o.r0 = b4[64 + cg * 2]; o.r1 = b4[64 + cg * 2 + 1];
;         o.v = cb[sl * 384 + vo];
;       };
;       float ykeep = 0.f;
;       auto step = [&](const ScanOps& o, int sl) {
;         const f32x4 sA = S0 * o.nkk0 + S1 * o.nkk1;
;         const float sa = red8((sA[0] + sA[1]) + (sA[2] + sA[3]));
;         S0 = S0 * o.w0 + (o.kka0 * sa + o.kd0 * o.v);
;         S1 = S1 * o.w1 + (o.kka1 * sa + o.kd1 * o.v);
;         const f32x4 yA = S0 * o.r0 + S1 * o.r1;
;         const float y = red8((yA[0] + yA[1]) + (yA[2] + yA[3]));
;         ykeep = (cg == (sl & 7)) ? y : ykeep;
;       };
;       ScanOps oa, ob;
;       ldops(oa, 0);
; #pragma unroll
;       for (int s8 = 0; s8 < 32; s8 += 8) {
; #pragma unroll
;         for (int q = 0; q < 8; q += 2) {
;           ldops(ob, s8 + q + 1);
;           step(oa, s8 + q);
;           ldops(oa, (s8 + q + 2) & 31);
;           step(ob, s8 + q + 1);
;         }
;         yw[s8 * 32] = ykeep;
	ds_read_b128 v[28:31], v78 offset:32256
	ds_read_b128 v[32:35], v78 offset:32512
	ds_read_b128 v[36:39], v78 offset:32768
	ds_read_b128 v[40:43], v78 offset:33024
	ds_read_b128 v[44:47], v78 offset:33280
	v_pk_mul_f32 v[56:57], v[0:1], v[8:9]
	v_pk_mul_f32 v[58:59], v[4:5], v[8:9]
	v_pk_fma_f32 v[56:57], v[2:3], v[10:11], v[56:57]
	v_pk_fma_f32 v[58:59], v[6:7], v[10:11], v[58:59]
	v_add_f32_e32 v72, v56, v57
	v_add_f32_e32 v73, v58, v59
	v_pk_mul_f32 v[64:65], v[20:21], v[48:49] op_sel_hi:[1,0]
	v_pk_mul_f32 v[68:69], v[20:21], v[52:53] op_sel_hi:[1,0]
	v_add_f32_dpp v74, v73, v72 row_mirror row_mask:0xf bank_mask:0xf bound_ctrl:1
	v_pk_mul_f32 v[66:67], v[22:23], v[48:49] op_sel_hi:[1,0]
	v_pk_mul_f32 v[70:71], v[22:23], v[52:53] op_sel_hi:[1,0]
	v_add_f32_dpp v74, v74, v74 quad_perm:[1,0,3,2] row_mask:0xf bank_mask:0xf bound_ctrl:1
	v_pk_fma_f32 v[0:1], v[0:1], v[12:13], v[64:65]
	v_pk_fma_f32 v[4:5], v[4:5], v[12:13], v[68:69]
	v_add_f32_dpp v74, v74, v74 quad_perm:[2,3,0,1] row_mask:0xf bank_mask:0xf bound_ctrl:1
	v_pk_fma_f32 v[2:3], v[2:3], v[14:15], v[66:67]
	v_pk_fma_f32 v[6:7], v[6:7], v[14:15], v[70:71]
	v_add_f32_dpp v74, v74, v74 row_half_mirror row_mask:0xf bank_mask:0xf bound_ctrl:1
	v_pk_fma_f32 v[0:1], v[16:17], v[74:75], v[0:1] op_sel_hi:[1,0,1]
	v_pk_fma_f32 v[2:3], v[18:19], v[74:75], v[2:3] op_sel_hi:[1,0,1]
	v_mov_b32_dpp v76, v74 row_mirror row_mask:0xf bank_mask:0xf bound_ctrl:1
	v_pk_mul_f32 v[60:61], v[0:1], v[24:25]
	v_pk_fma_f32 v[4:5], v[16:17], v[76:77], v[4:5] op_sel_hi:[1,0,1]
	v_pk_fma_f32 v[6:7], v[18:19], v[76:77], v[6:7] op_sel_hi:[1,0,1]
	v_pk_fma_f32 v[60:61], v[2:3], v[26:27], v[60:61]
	v_pk_mul_f32 v[62:63], v[4:5], v[24:25]
	v_pk_fma_f32 v[62:63], v[6:7], v[26:27], v[62:63]
	v_add_f32_e32 v102, v60, v61
	v_add_f32_e32 v118, v62, v63
	s_waitcnt lgkmcnt(0)
	ds_read_b128 v[8:11], v78 offset:33792
	ds_read_b128 v[12:15], v78 offset:34048
	ds_read_b128 v[16:19], v78 offset:34304
	ds_read_b128 v[20:23], v78 offset:34560
	ds_read_b128 v[24:27], v78 offset:34816
	ds_read2st64_b32 v[50:51], v79 offset0:137 offset1:143
	ds_read2st64_b32 v[54:55], v81 offset0:137 offset1:143
	v_pk_mul_f32 v[56:57], v[0:1], v[28:29]
	v_pk_mul_f32 v[58:59], v[4:5], v[28:29]
	v_pk_fma_f32 v[56:57], v[2:3], v[30:31], v[56:57]
	v_pk_fma_f32 v[58:59], v[6:7], v[30:31], v[58:59]
	v_add_f32_e32 v72, v56, v57
	v_add_f32_e32 v73, v58, v59
	v_pk_mul_f32 v[64:65], v[40:41], v[48:49] op_sel:[0,1] op_sel_hi:[1,1]
	v_pk_mul_f32 v[68:69], v[40:41], v[52:53] op_sel:[0,1] op_sel_hi:[1,1]
	v_add_f32_dpp v74, v73, v72 row_mirror row_mask:0xf bank_mask:0xf bound_ctrl:1
	v_pk_mul_f32 v[66:67], v[42:43], v[48:49] op_sel:[0,1] op_sel_hi:[1,1]
	v_pk_mul_f32 v[70:71], v[42:43], v[52:53] op_sel:[0,1] op_sel_hi:[1,1]
	v_add_f32_dpp v74, v74, v74 quad_perm:[1,0,3,2] row_mask:0xf bank_mask:0xf bound_ctrl:1
	v_pk_fma_f32 v[0:1], v[0:1], v[32:33], v[64:65]
	v_pk_fma_f32 v[4:5], v[4:5], v[32:33], v[68:69]
	v_add_f32_dpp v74, v74, v74 quad_perm:[2,3,0,1] row_mask:0xf bank_mask:0xf bound_ctrl:1
	v_pk_fma_f32 v[2:3], v[2:3], v[34:35], v[66:67]
	v_pk_fma_f32 v[6:7], v[6:7], v[34:35], v[70:71]
	v_add_f32_dpp v74, v74, v74 row_half_mirror row_mask:0xf bank_mask:0xf bound_ctrl:1
	v_pk_fma_f32 v[0:1], v[36:37], v[74:75], v[0:1] op_sel_hi:[1,0,1]
	v_pk_fma_f32 v[2:3], v[38:39], v[74:75], v[2:3] op_sel_hi:[1,0,1]
	v_mov_b32_dpp v76, v74 row_mirror row_mask:0xf bank_mask:0xf bound_ctrl:1
	v_pk_mul_f32 v[60:61], v[0:1], v[44:45]
	v_pk_fma_f32 v[4:5], v[36:37], v[76:77], v[4:5] op_sel_hi:[1,0,1]
	v_pk_fma_f32 v[6:7], v[38:39], v[76:77], v[6:7] op_sel_hi:[1,0,1]
	v_pk_fma_f32 v[60:61], v[2:3], v[46:47], v[60:61]
	v_pk_mul_f32 v[62:63], v[4:5], v[44:45]
	v_pk_fma_f32 v[62:63], v[6:7], v[46:47], v[62:63]
	v_add_f32_e32 v103, v60, v61
	v_add_f32_e32 v119, v62, v63
	s_waitcnt lgkmcnt(0)
	ds_read_b128 v[28:31], v78 offset:35328
	ds_read_b128 v[32:35], v78 offset:35584
	ds_read_b128 v[36:39], v78 offset:35840
	ds_read_b128 v[40:43], v78 offset:36096
	ds_read_b128 v[44:47], v78 offset:36352
	v_pk_mul_f32 v[56:57], v[0:1], v[8:9]
	v_pk_mul_f32 v[58:59], v[4:5], v[8:9]
	v_pk_fma_f32 v[56:57], v[2:3], v[10:11], v[56:57]
	v_pk_fma_f32 v[58:59], v[6:7], v[10:11], v[58:59]
	v_add_f32_e32 v72, v56, v57
	v_add_f32_e32 v73, v58, v59
	v_pk_mul_f32 v[64:65], v[20:21], v[50:51] op_sel_hi:[1,0]
	v_pk_mul_f32 v[68:69], v[20:21], v[54:55] op_sel_hi:[1,0]
	v_add_f32_dpp v74, v73, v72 row_mirror row_mask:0xf bank_mask:0xf bound_ctrl:1
	v_pk_mul_f32 v[66:67], v[22:23], v[50:51] op_sel_hi:[1,0]
	v_pk_mul_f32 v[70:71], v[22:23], v[54:55] op_sel_hi:[1,0]
	v_add_f32_dpp v74, v74, v74 quad_perm:[1,0,3,2] row_mask:0xf bank_mask:0xf bound_ctrl:1
	v_pk_fma_f32 v[0:1], v[0:1], v[12:13], v[64:65]
	v_pk_fma_f32 v[4:5], v[4:5], v[12:13], v[68:69]
	v_add_f32_dpp v74, v74, v74 quad_perm:[2,3,0,1] row_mask:0xf bank_mask:0xf bound_ctrl:1
	v_pk_fma_f32 v[2:3], v[2:3], v[14:15], v[66:67]
	v_pk_fma_f32 v[6:7], v[6:7], v[14:15], v[70:71]
	v_add_f32_dpp v74, v74, v74 row_half_mirror row_mask:0xf bank_mask:0xf bound_ctrl:1
	v_pk_fma_f32 v[0:1], v[16:17], v[74:75], v[0:1] op_sel_hi:[1,0,1]
	v_pk_fma_f32 v[2:3], v[18:19], v[74:75], v[2:3] op_sel_hi:[1,0,1]
	v_mov_b32_dpp v76, v74 row_mirror row_mask:0xf bank_mask:0xf bound_ctrl:1
	v_pk_mul_f32 v[60:61], v[0:1], v[24:25]
	v_pk_fma_f32 v[4:5], v[16:17], v[76:77], v[4:5] op_sel_hi:[1,0,1]
	v_pk_fma_f32 v[6:7], v[18:19], v[76:77], v[6:7] op_sel_hi:[1,0,1]
	v_pk_fma_f32 v[60:61], v[2:3], v[26:27], v[60:61]
	v_pk_mul_f32 v[62:63], v[4:5], v[24:25]
	v_pk_fma_f32 v[62:63], v[6:7], v[26:27], v[62:63]
	v_add_f32_e32 v104, v60, v61
	v_add_f32_e32 v120, v62, v63
	s_waitcnt lgkmcnt(0)
; DEV void scan_tile(const Params& p, int l, int tile, char* smem) {
;     ...
;       auto ldops = [&](ScanOps& o, int sl) {
;         const f32x4* b4 = (const f32x4*)(cb + sl * 384);
;         o.nkk0 = b4[cg * 2]; o.nkk1 = b4[cg * 2 + 1];
;         o.w0 = b4[16 + cg * 2]; o.w1 = b4[16 + cg * 2 + 1];
;         o.kka0 = b4[32 + cg * 2]; o.kka1 = b4[32 + cg * 2 + 1];
;         o.kd0 = b4[48 + cg * 2]; o.kd1 = b4[48 + cg * 2 + 1];
;         o.r0 = b4[64 + cg * 2]; o.r1 = b4[64 + cg * 2 + 1];
;         o.v = cb[sl * 384 + vo];
;       };
;       float ykeep = 0.f;
;       auto step = [&](const ScanOps& o, int sl) {
;         const f32x4 sA = S0 * o.nkk0 + S1 * o.nkk1;
;         const float sa = red8((sA[0] + sA[1]) + (sA[2] + sA[3]));
;         S0 = S0 * o.w0 + (o.kka0 * sa + o.kd0 * o.v);
;         S1 = S1 * o.w1 + (o.kka1 * sa + o.kd1 * o.v);
;         const f32x4 yA = S0 * o.r0 + S1 * o.r1;
;         const float y = red8((yA[0] + yA[1]) + (yA[2] + yA[3]));
;         ykeep = (cg == (sl & 7)) ? y : ykeep;
;       };
;       ScanOps oa, ob;
;       ldops(oa, 0);
; #pragma unroll
;       for (int s8 = 0; s8 < 32; s8 += 8) {
; #pragma unroll
;         for (int q = 0; q < 8; q += 2) {
;           ldops(ob, s8 + q + 1);
;           step(oa, s8 + q);
;           ldops(oa, (s8 + q + 2) & 31);
;           step(ob, s8 + q + 1);
;         }
;         yw[s8 * 32] = ykeep;
	ds_read_b128 v[8:11], v78 offset:36864
	ds_read_b128 v[12:15], v78 offset:37120
	ds_read_b128 v[16:19], v78 offset:37376
	ds_read_b128 v[20:23], v78 offset:37632
	ds_read_b128 v[24:27], v78 offset:37888
	ds_read2st64_b32 v[48:49], v79 offset0:149 offset1:155
	ds_read2st64_b32 v[52:53], v81 offset0:149 offset1:155
	v_pk_mul_f32 v[56:57], v[0:1], v[28:29]
	v_pk_mul_f32 v[58:59], v[4:5], v[28:29]
	v_pk_fma_f32 v[56:57], v[2:3], v[30:31], v[56:57]
	v_pk_fma_f32 v[58:59], v[6:7], v[30:31], v[58:59]
	v_add_f32_e32 v72, v56, v57
	v_add_f32_e32 v73, v58, v59
	v_pk_mul_f32 v[64:65], v[40:41], v[50:51] op_sel:[0,1] op_sel_hi:[1,1]
	v_pk_mul_f32 v[68:69], v[40:41], v[54:55] op_sel:[0,1] op_sel_hi:[1,1]
	v_add_f32_dpp v74, v73, v72 row_mirror row_mask:0xf bank_mask:0xf bound_ctrl:1
	v_pk_mul_f32 v[66:67], v[42:43], v[50:51] op_sel:[0,1] op_sel_hi:[1,1]
	v_pk_mul_f32 v[70:71], v[42:43], v[54:55] op_sel:[0,1] op_sel_hi:[1,1]
	v_add_f32_dpp v74, v74, v74 quad_perm:[1,0,3,2] row_mask:0xf bank_mask:0xf bound_ctrl:1
	v_pk_fma_f32 v[0:1], v[0:1], v[32:33], v[64:65]
	v_pk_fma_f32 v[4:5], v[4:5], v[32:33], v[68:69]
	v_add_f32_dpp v74, v74, v74 quad_perm:[2,3,0,1] row_mask:0xf bank_mask:0xf bound_ctrl:1
	v_pk_fma_f32 v[2:3], v[2:3], v[34:35], v[66:67]
	v_pk_fma_f32 v[6:7], v[6:7], v[34:35], v[70:71]
	v_add_f32_dpp v74, v74, v74 row_half_mirror row_mask:0xf bank_mask:0xf bound_ctrl:1
	v_pk_fma_f32 v[0:1], v[36:37], v[74:75], v[0:1] op_sel_hi:[1,0,1]
	v_pk_fma_f32 v[2:3], v[38:39], v[74:75], v[2:3] op_sel_hi:[1,0,1]
	v_mov_b32_dpp v76, v74 row_mirror row_mask:0xf bank_mask:0xf bound_ctrl:1
	v_pk_mul_f32 v[60:61], v[0:1], v[44:45]
	v_pk_fma_f32 v[4:5], v[36:37], v[76:77], v[4:5] op_sel_hi:[1,0,1]
	v_pk_fma_f32 v[6:7], v[38:39], v[76:77], v[6:7] op_sel_hi:[1,0,1]
	v_pk_fma_f32 v[60:61], v[2:3], v[46:47], v[60:61]
	v_pk_mul_f32 v[62:63], v[4:5], v[44:45]
	v_pk_fma_f32 v[62:63], v[6:7], v[46:47], v[62:63]
	v_add_f32_e32 v105, v60, v61
	v_add_f32_e32 v121, v62, v63
	s_waitcnt lgkmcnt(0)
	ds_read_b128 v[28:31], v78 offset:38400
	ds_read_b128 v[32:35], v78 offset:38656
	ds_read_b128 v[36:39], v78 offset:38912
	ds_read_b128 v[40:43], v78 offset:39168
	ds_read_b128 v[44:47], v78 offset:39424
	v_pk_mul_f32 v[56:57], v[0:1], v[8:9]
	v_pk_mul_f32 v[58:59], v[4:5], v[8:9]
	v_pk_fma_f32 v[56:57], v[2:3], v[10:11], v[56:57]
	v_pk_fma_f32 v[58:59], v[6:7], v[10:11], v[58:59]
	v_add_f32_e32 v72, v56, v57
	v_add_f32_e32 v73, v58, v59
	v_pk_mul_f32 v[64:65], v[20:21], v[48:49] op_sel_hi:[1,0]
	v_pk_mul_f32 v[68:69], v[20:21], v[52:53] op_sel_hi:[1,0]
	v_add_f32_dpp v74, v73, v72 row_mirror row_mask:0xf bank_mask:0xf bound_ctrl:1
	v_pk_mul_f32 v[66:67], v[22:23], v[48:49] op_sel_hi:[1,0]
	v_pk_mul_f32 v[70:71], v[22:23], v[52:53] op_sel_hi:[1,0]
	v_add_f32_dpp v74, v74, v74 quad_perm:[1,0,3,2] row_mask:0xf bank_mask:0xf bound_ctrl:1
	v_pk_fma_f32 v[0:1], v[0:1], v[12:13], v[64:65]
	v_pk_fma_f32 v[4:5], v[4:5], v[12:13], v[68:69]
	v_add_f32_dpp v74, v74, v74 quad_perm:[2,3,0,1] row_mask:0xf bank_mask:0xf bound_ctrl:1
	v_pk_fma_f32 v[2:3], v[2:3], v[14:15], v[66:67]
	v_pk_fma_f32 v[6:7], v[6:7], v[14:15], v[70:71]
	v_add_f32_dpp v74, v74, v74 row_half_mirror row_mask:0xf bank_mask:0xf bound_ctrl:1
	v_pk_fma_f32 v[0:1], v[16:17], v[74:75], v[0:1] op_sel_hi:[1,0,1]
	v_pk_fma_f32 v[2:3], v[18:19], v[74:75], v[2:3] op_sel_hi:[1,0,1]
	v_mov_b32_dpp v76, v74 row_mirror row_mask:0xf bank_mask:0xf bound_ctrl:1
	v_pk_mul_f32 v[60:61], v[0:1], v[24:25]
	v_pk_fma_f32 v[4:5], v[16:17], v[76:77], v[4:5] op_sel_hi:[1,0,1]
	v_pk_fma_f32 v[6:7], v[18:19], v[76:77], v[6:7] op_sel_hi:[1,0,1]
	v_pk_fma_f32 v[60:61], v[2:3], v[26:27], v[60:61]
	v_pk_mul_f32 v[62:63], v[4:5], v[24:25]
	v_pk_fma_f32 v[62:63], v[6:7], v[26:27], v[62:63]
	v_add_f32_e32 v106, v60, v61
	v_add_f32_e32 v122, v62, v63
	s_waitcnt lgkmcnt(0)
	ds_read_b128 v[8:11], v78 offset:39936
	ds_read_b128 v[12:15], v78 offset:40192
	ds_read_b128 v[16:19], v78 offset:40448
	ds_read_b128 v[20:23], v78 offset:40704
	ds_read_b128 v[24:27], v78 offset:40960
	ds_read2st64_b32 v[50:51], v79 offset0:161 offset1:167
	ds_read2st64_b32 v[54:55], v81 offset0:161 offset1:167
	v_pk_mul_f32 v[56:57], v[0:1], v[28:29]
	v_pk_mul_f32 v[58:59], v[4:5], v[28:29]
	v_pk_fma_f32 v[56:57], v[2:3], v[30:31], v[56:57]
	v_pk_fma_f32 v[58:59], v[6:7], v[30:31], v[58:59]
	v_add_f32_e32 v72, v56, v57
	v_add_f32_e32 v73, v58, v59
	v_pk_mul_f32 v[64:65], v[40:41], v[48:49] op_sel:[0,1] op_sel_hi:[1,1]
	v_pk_mul_f32 v[68:69], v[40:41], v[52:53] op_sel:[0,1] op_sel_hi:[1,1]
	v_add_f32_dpp v74, v73, v72 row_mirror row_mask:0xf bank_mask:0xf bound_ctrl:1
	v_pk_mul_f32 v[66:67], v[42:43], v[48:49] op_sel:[0,1] op_sel_hi:[1,1]
	v_pk_mul_f32 v[70:71], v[42:43], v[52:53] op_sel:[0,1] op_sel_hi:[1,1]
	v_add_f32_dpp v74, v74, v74 quad_perm:[1,0,3,2] row_mask:0xf bank_mask:0xf bound_ctrl:1
	v_pk_fma_f32 v[0:1], v[0:1], v[32:33], v[64:65]
	v_pk_fma_f32 v[4:5], v[4:5], v[32:33], v[68:69]
	v_add_f32_dpp v74, v74, v74 quad_perm:[2,3,0,1] row_mask:0xf bank_mask:0xf bound_ctrl:1
	v_pk_fma_f32 v[2:3], v[2:3], v[34:35], v[66:67]
	v_pk_fma_f32 v[6:7], v[6:7], v[34:35], v[70:71]
	v_add_f32_dpp v74, v74, v74 row_half_mirror row_mask:0xf bank_mask:0xf bound_ctrl:1
	v_pk_fma_f32 v[0:1], v[36:37], v[74:75], v[0:1] op_sel_hi:[1,0,1]
	v_pk_fma_f32 v[2:3], v[38:39], v[74:75], v[2:3] op_sel_hi:[1,0,1]
	v_mov_b32_dpp v76, v74 row_mirror row_mask:0xf bank_mask:0xf bound_ctrl:1
	v_pk_mul_f32 v[60:61], v[0:1], v[44:45]
	v_pk_fma_f32 v[4:5], v[36:37], v[76:77], v[4:5] op_sel_hi:[1,0,1]
	v_pk_fma_f32 v[6:7], v[38:39], v[76:77], v[6:7] op_sel_hi:[1,0,1]
	v_pk_fma_f32 v[60:61], v[2:3], v[46:47], v[60:61]
	v_pk_mul_f32 v[62:63], v[4:5], v[44:45]
	v_pk_fma_f32 v[62:63], v[6:7], v[46:47], v[62:63]
	v_add_f32_e32 v107, v60, v61
	v_add_f32_e32 v123, v62, v63
	s_waitcnt lgkmcnt(0)
; DEV void scan_tile(const Params& p, int l, int tile, char* smem) {
;     ...
;       auto ldops = [&](ScanOps& o, int sl) {
;         const f32x4* b4 = (const f32x4*)(cb + sl * 384);
;         o.nkk0 = b4[cg * 2]; o.nkk1 = b4[cg * 2 + 1];
;         o.w0 = b4[16 + cg * 2]; o.w1 = b4[16 + cg * 2 + 1];
;         o.kka0 = b4[32 + cg * 2]; o.kka1 = b4[32 + cg * 2 + 1];
;         o.kd0 = b4[48 + cg * 2]; o.kd1 = b4[48 + cg * 2 + 1];
;         o.r0 = b4[64 + cg * 2]; o.r1 = b4[64 + cg * 2 + 1];
;         o.v = cb[sl * 384 + vo];
;       };
;       float ykeep = 0.f;
;       auto step = [&](const ScanOps& o, int sl) {
;         const f32x4 sA = S0 * o.nkk0 + S1 * o.nkk1;
;         const float sa = red8((sA[0] + sA[1]) + (sA[2] + sA[3]));
;         S0 = S0 * o.w0 + (o.kka0 * sa + o.kd0 * o.v);
;         S1 = S1 * o.w1 + (o.kka1 * sa + o.kd1 * o.v);
;         const f32x4 yA = S0 * o.r0 + S1 * o.r1;
;         const float y = red8((yA[0] + yA[1]) + (yA[2] + yA[3]));
;         ykeep = (cg == (sl & 7)) ? y : ykeep;
;       };
;       ScanOps oa, ob;
;       ldops(oa, 0);
; #pragma unroll
;       for (int s8 = 0; s8 < 32; s8 += 8) {
; #pragma unroll
;         for (int q = 0; q < 8; q += 2) {
;           ldops(ob, s8 + q + 1);
;           step(oa, s8 + q);
;           ldops(oa, (s8 + q + 2) & 31);
;           step(ob, s8 + q + 1);
;         }
;         yw[s8 * 32] = ykeep;
	ds_read_b128 v[28:31], v78 offset:41472
	ds_read_b128 v[32:35], v78 offset:41728
	ds_read_b128 v[36:39], v78 offset:41984
	ds_read_b128 v[40:43], v78 offset:42240
	ds_read_b128 v[44:47], v78 offset:42496
	v_pk_mul_f32 v[56:57], v[0:1], v[8:9]
	v_pk_mul_f32 v[58:59], v[4:5], v[8:9]
	v_pk_fma_f32 v[56:57], v[2:3], v[10:11], v[56:57]
	v_pk_fma_f32 v[58:59], v[6:7], v[10:11], v[58:59]
	v_add_f32_e32 v72, v56, v57
	v_add_f32_e32 v73, v58, v59
	v_pk_mul_f32 v[64:65], v[20:21], v[50:51] op_sel_hi:[1,0]
	v_pk_mul_f32 v[68:69], v[20:21], v[54:55] op_sel_hi:[1,0]
	v_add_f32_dpp v74, v73, v72 row_mirror row_mask:0xf bank_mask:0xf bound_ctrl:1
	v_pk_mul_f32 v[66:67], v[22:23], v[50:51] op_sel_hi:[1,0]
	v_pk_mul_f32 v[70:71], v[22:23], v[54:55] op_sel_hi:[1,0]
	v_add_f32_dpp v74, v74, v74 quad_perm:[1,0,3,2] row_mask:0xf bank_mask:0xf bound_ctrl:1
	v_pk_fma_f32 v[0:1], v[0:1], v[12:13], v[64:65]
	v_pk_fma_f32 v[4:5], v[4:5], v[12:13], v[68:69]
	v_add_f32_dpp v74, v74, v74 quad_perm:[2,3,0,1] row_mask:0xf bank_mask:0xf bound_ctrl:1
	v_pk_fma_f32 v[2:3], v[2:3], v[14:15], v[66:67]
	v_pk_fma_f32 v[6:7], v[6:7], v[14:15], v[70:71]
	v_add_f32_dpp v74, v74, v74 row_half_mirror row_mask:0xf bank_mask:0xf bound_ctrl:1
	v_pk_fma_f32 v[0:1], v[16:17], v[74:75], v[0:1] op_sel_hi:[1,0,1]
	v_pk_fma_f32 v[2:3], v[18:19], v[74:75], v[2:3] op_sel_hi:[1,0,1]
	v_mov_b32_dpp v76, v74 row_mirror row_mask:0xf bank_mask:0xf bound_ctrl:1
	v_pk_mul_f32 v[60:61], v[0:1], v[24:25]
	v_pk_fma_f32 v[4:5], v[16:17], v[76:77], v[4:5] op_sel_hi:[1,0,1]
	v_pk_fma_f32 v[6:7], v[18:19], v[76:77], v[6:7] op_sel_hi:[1,0,1]
	v_pk_fma_f32 v[60:61], v[2:3], v[26:27], v[60:61]
	v_pk_mul_f32 v[62:63], v[4:5], v[24:25]
	v_pk_fma_f32 v[62:63], v[6:7], v[26:27], v[62:63]
	v_add_f32_e32 v108, v60, v61
	v_add_f32_e32 v124, v62, v63
	s_waitcnt lgkmcnt(0)
	ds_read_b128 v[8:11], v78 offset:43008
	ds_read_b128 v[12:15], v78 offset:43264
	ds_read_b128 v[16:19], v78 offset:43520
	ds_read_b128 v[20:23], v78 offset:43776
	ds_read_b128 v[24:27], v78 offset:44032
	ds_read2st64_b32 v[48:49], v79 offset0:173 offset1:179
	ds_read2st64_b32 v[52:53], v81 offset0:173 offset1:179
	v_pk_mul_f32 v[56:57], v[0:1], v[28:29]
	v_pk_mul_f32 v[58:59], v[4:5], v[28:29]
	v_pk_fma_f32 v[56:57], v[2:3], v[30:31], v[56:57]
	v_pk_fma_f32 v[58:59], v[6:7], v[30:31], v[58:59]
	v_add_f32_e32 v72, v56, v57
	v_add_f32_e32 v73, v58, v59
	v_pk_mul_f32 v[64:65], v[40:41], v[50:51] op_sel:[0,1] op_sel_hi:[1,1]
	v_pk_mul_f32 v[68:69], v[40:41], v[54:55] op_sel:[0,1] op_sel_hi:[1,1]
	v_add_f32_dpp v74, v73, v72 row_mirror row_mask:0xf bank_mask:0xf bound_ctrl:1
	v_pk_mul_f32 v[66:67], v[42:43], v[50:51] op_sel:[0,1] op_sel_hi:[1,1]
	v_pk_mul_f32 v[70:71], v[42:43], v[54:55] op_sel:[0,1] op_sel_hi:[1,1]
	v_add_f32_dpp v74, v74, v74 quad_perm:[1,0,3,2] row_mask:0xf bank_mask:0xf bound_ctrl:1
	v_pk_fma_f32 v[0:1], v[0:1], v[32:33], v[64:65]
	v_pk_fma_f32 v[4:5], v[4:5], v[32:33], v[68:69]
	v_add_f32_dpp v74, v74, v74 quad_perm:[2,3,0,1] row_mask:0xf bank_mask:0xf bound_ctrl:1
	v_pk_fma_f32 v[2:3], v[2:3], v[34:35], v[66:67]
	v_pk_fma_f32 v[6:7], v[6:7], v[34:35], v[70:71]
	v_add_f32_dpp v74, v74, v74 row_half_mirror row_mask:0xf bank_mask:0xf bound_ctrl:1
	v_pk_fma_f32 v[0:1], v[36:37], v[74:75], v[0:1] op_sel_hi:[1,0,1]
	v_pk_fma_f32 v[2:3], v[38:39], v[74:75], v[2:3] op_sel_hi:[1,0,1]
	v_mov_b32_dpp v76, v74 row_mirror row_mask:0xf bank_mask:0xf bound_ctrl:1
	v_pk_mul_f32 v[60:61], v[0:1], v[44:45]
	v_pk_fma_f32 v[4:5], v[36:37], v[76:77], v[4:5] op_sel_hi:[1,0,1]
	v_pk_fma_f32 v[6:7], v[38:39], v[76:77], v[6:7] op_sel_hi:[1,0,1]
	v_pk_fma_f32 v[60:61], v[2:3], v[46:47], v[60:61]
	v_pk_mul_f32 v[62:63], v[4:5], v[44:45]
	v_pk_fma_f32 v[62:63], v[6:7], v[46:47], v[62:63]
	v_add_f32_e32 v109, v60, v61
	v_add_f32_e32 v125, v62, v63
	s_waitcnt lgkmcnt(0)
	ds_read_b128 v[28:31], v78 offset:44544
	ds_read_b128 v[32:35], v78 offset:44800
	ds_read_b128 v[36:39], v78 offset:45056
	ds_read_b128 v[40:43], v78 offset:45312
	ds_read_b128 v[44:47], v78 offset:45568
	v_pk_mul_f32 v[56:57], v[0:1], v[8:9]
	v_pk_mul_f32 v[58:59], v[4:5], v[8:9]
	v_pk_fma_f32 v[56:57], v[2:3], v[10:11], v[56:57]
	v_pk_fma_f32 v[58:59], v[6:7], v[10:11], v[58:59]
	v_add_f32_e32 v72, v56, v57
	v_add_f32_e32 v73, v58, v59
	v_pk_mul_f32 v[64:65], v[20:21], v[48:49] op_sel_hi:[1,0]
	v_pk_mul_f32 v[68:69], v[20:21], v[52:53] op_sel_hi:[1,0]
	v_add_f32_dpp v74, v73, v72 row_mirror row_mask:0xf bank_mask:0xf bound_ctrl:1
	v_pk_mul_f32 v[66:67], v[22:23], v[48:49] op_sel_hi:[1,0]
	v_pk_mul_f32 v[70:71], v[22:23], v[52:53] op_sel_hi:[1,0]
	v_add_f32_dpp v74, v74, v74 quad_perm:[1,0,3,2] row_mask:0xf bank_mask:0xf bound_ctrl:1
	v_pk_fma_f32 v[0:1], v[0:1], v[12:13], v[64:65]
	v_pk_fma_f32 v[4:5], v[4:5], v[12:13], v[68:69]
	v_add_f32_dpp v74, v74, v74 quad_perm:[2,3,0,1] row_mask:0xf bank_mask:0xf bound_ctrl:1
	v_pk_fma_f32 v[2:3], v[2:3], v[14:15], v[66:67]
	v_pk_fma_f32 v[6:7], v[6:7], v[14:15], v[70:71]
	v_add_f32_dpp v74, v74, v74 row_half_mirror row_mask:0xf bank_mask:0xf bound_ctrl:1
	v_pk_fma_f32 v[0:1], v[16:17], v[74:75], v[0:1] op_sel_hi:[1,0,1]
	v_pk_fma_f32 v[2:3], v[18:19], v[74:75], v[2:3] op_sel_hi:[1,0,1]
	v_mov_b32_dpp v76, v74 row_mirror row_mask:0xf bank_mask:0xf bound_ctrl:1
	v_pk_mul_f32 v[60:61], v[0:1], v[24:25]
	v_pk_fma_f32 v[4:5], v[16:17], v[76:77], v[4:5] op_sel_hi:[1,0,1]
	v_pk_fma_f32 v[6:7], v[18:19], v[76:77], v[6:7] op_sel_hi:[1,0,1]
	v_pk_fma_f32 v[60:61], v[2:3], v[26:27], v[60:61]
	v_pk_mul_f32 v[62:63], v[4:5], v[24:25]
	v_pk_fma_f32 v[62:63], v[6:7], v[26:27], v[62:63]
	v_add_f32_e32 v110, v60, v61
	v_add_f32_e32 v126, v62, v63
	s_waitcnt lgkmcnt(0)
; DEV void scan_tile(const Params& p, int l, int tile, char* smem) {
;     ...
;       auto step = [&](const ScanOps& o, int sl) {
;         const f32x4 sA = S0 * o.nkk0 + S1 * o.nkk1;
;         const float sa = red8((sA[0] + sA[1]) + (sA[2] + sA[3]));
;         S0 = S0 * o.w0 + (o.kka0 * sa + o.kd0 * o.v);
;         S1 = S1 * o.w1 + (o.kka1 * sa + o.kd1 * o.v);
;         const f32x4 yA = S0 * o.r0 + S1 * o.r1;
;         const float y = red8((yA[0] + yA[1]) + (yA[2] + yA[3]));
;         ykeep = (cg == (sl & 7)) ? y : ykeep;
;       };
;       ScanOps oa, ob;
;       ldops(oa, 0);
; #pragma unroll
;       for (int s8 = 0; s8 < 32; s8 += 8) {
; #pragma unroll
;         for (int q = 0; q < 8; q += 2) {
;           ldops(ob, s8 + q + 1);
;           step(oa, s8 + q);
;           ldops(oa, (s8 + q + 2) & 31);
;           step(ob, s8 + q + 1);
;         }
;         yw[s8 * 32] = ykeep;
	ds_read_b128 v[8:11], v78 offset:46080
	ds_read_b128 v[12:15], v78 offset:46336
	ds_read_b128 v[16:19], v78 offset:46592
	ds_read_b128 v[20:23], v78 offset:46848
	ds_read_b128 v[24:27], v78 offset:47104
	ds_read2st64_b32 v[50:51], v79 offset0:185 offset1:191
	ds_read2st64_b32 v[54:55], v81 offset0:185 offset1:191
	v_pk_mul_f32 v[56:57], v[0:1], v[28:29]
	v_pk_mul_f32 v[58:59], v[4:5], v[28:29]
	v_pk_fma_f32 v[56:57], v[2:3], v[30:31], v[56:57]
	v_pk_fma_f32 v[58:59], v[6:7], v[30:31], v[58:59]
	v_add_f32_e32 v72, v56, v57
	v_add_f32_e32 v73, v58, v59
	v_pk_mul_f32 v[64:65], v[40:41], v[48:49] op_sel:[0,1] op_sel_hi:[1,1]
	v_pk_mul_f32 v[68:69], v[40:41], v[52:53] op_sel:[0,1] op_sel_hi:[1,1]
	v_add_f32_dpp v74, v73, v72 row_mirror row_mask:0xf bank_mask:0xf bound_ctrl:1
	v_pk_mul_f32 v[66:67], v[42:43], v[48:49] op_sel:[0,1] op_sel_hi:[1,1]
	v_pk_mul_f32 v[70:71], v[42:43], v[52:53] op_sel:[0,1] op_sel_hi:[1,1]
	v_add_f32_dpp v74, v74, v74 quad_perm:[1,0,3,2] row_mask:0xf bank_mask:0xf bound_ctrl:1
	v_pk_fma_f32 v[0:1], v[0:1], v[32:33], v[64:65]
	v_pk_fma_f32 v[4:5], v[4:5], v[32:33], v[68:69]
	v_add_f32_dpp v74, v74, v74 quad_perm:[2,3,0,1] row_mask:0xf bank_mask:0xf bound_ctrl:1
	v_pk_fma_f32 v[2:3], v[2:3], v[34:35], v[66:67]
	v_pk_fma_f32 v[6:7], v[6:7], v[34:35], v[70:71]
	v_add_f32_dpp v74, v74, v74 row_half_mirror row_mask:0xf bank_mask:0xf bound_ctrl:1
	v_pk_fma_f32 v[0:1], v[36:37], v[74:75], v[0:1] op_sel_hi:[1,0,1]
	v_pk_fma_f32 v[2:3], v[38:39], v[74:75], v[2:3] op_sel_hi:[1,0,1]
	v_mov_b32_dpp v76, v74 row_mirror row_mask:0xf bank_mask:0xf bound_ctrl:1
	v_pk_mul_f32 v[60:61], v[0:1], v[44:45]
	v_pk_fma_f32 v[4:5], v[36:37], v[76:77], v[4:5] op_sel_hi:[1,0,1]
	v_pk_fma_f32 v[6:7], v[38:39], v[76:77], v[6:7] op_sel_hi:[1,0,1]
	v_pk_fma_f32 v[60:61], v[2:3], v[46:47], v[60:61]
	v_pk_mul_f32 v[62:63], v[4:5], v[44:45]
	v_pk_fma_f32 v[62:63], v[6:7], v[46:47], v[62:63]
	v_add_f32_e32 v111, v60, v61
	v_add_f32_e32 v127, v62, v63
	s_waitcnt lgkmcnt(0)
	ds_read_b128 v[28:31], v78 offset:47616
	ds_read_b128 v[32:35], v78 offset:47872
	ds_read_b128 v[36:39], v78 offset:48128
	ds_read_b128 v[40:43], v78 offset:48384
	ds_read_b128 v[44:47], v78 offset:48640
	v_pk_mul_f32 v[56:57], v[0:1], v[8:9]
	v_pk_mul_f32 v[58:59], v[4:5], v[8:9]
	v_pk_fma_f32 v[56:57], v[2:3], v[10:11], v[56:57]
	v_pk_fma_f32 v[58:59], v[6:7], v[10:11], v[58:59]
	v_add_f32_e32 v72, v56, v57
	v_add_f32_e32 v73, v58, v59
	v_pk_mul_f32 v[64:65], v[20:21], v[50:51] op_sel_hi:[1,0]
	v_pk_mul_f32 v[68:69], v[20:21], v[54:55] op_sel_hi:[1,0]
	v_add_f32_dpp v74, v73, v72 row_mirror row_mask:0xf bank_mask:0xf bound_ctrl:1
	v_pk_mul_f32 v[66:67], v[22:23], v[50:51] op_sel_hi:[1,0]
	v_pk_mul_f32 v[70:71], v[22:23], v[54:55] op_sel_hi:[1,0]
	v_add_f32_dpp v74, v74, v74 quad_perm:[1,0,3,2] row_mask:0xf bank_mask:0xf bound_ctrl:1
	v_pk_fma_f32 v[0:1], v[0:1], v[12:13], v[64:65]
	v_pk_fma_f32 v[4:5], v[4:5], v[12:13], v[68:69]
	v_add_f32_dpp v74, v74, v74 quad_perm:[2,3,0,1] row_mask:0xf bank_mask:0xf bound_ctrl:1
	v_pk_fma_f32 v[2:3], v[2:3], v[14:15], v[66:67]
	v_pk_fma_f32 v[6:7], v[6:7], v[14:15], v[70:71]
	v_add_f32_dpp v74, v74, v74 row_half_mirror row_mask:0xf bank_mask:0xf bound_ctrl:1
	v_pk_fma_f32 v[0:1], v[16:17], v[74:75], v[0:1] op_sel_hi:[1,0,1]
	v_pk_fma_f32 v[2:3], v[18:19], v[74:75], v[2:3] op_sel_hi:[1,0,1]
	v_mov_b32_dpp v76, v74 row_mirror row_mask:0xf bank_mask:0xf bound_ctrl:1
	v_pk_mul_f32 v[60:61], v[0:1], v[24:25]
	v_pk_fma_f32 v[4:5], v[16:17], v[76:77], v[4:5] op_sel_hi:[1,0,1]
	v_pk_fma_f32 v[6:7], v[18:19], v[76:77], v[6:7] op_sel_hi:[1,0,1]
	v_pk_fma_f32 v[60:61], v[2:3], v[26:27], v[60:61]
	v_pk_mul_f32 v[62:63], v[4:5], v[24:25]
	v_pk_fma_f32 v[62:63], v[6:7], v[26:27], v[62:63]
	v_add_f32_e32 v112, v60, v61
	v_add_f32_e32 v94, v62, v63
	s_waitcnt lgkmcnt(0)
	v_pk_mul_f32 v[56:57], v[0:1], v[28:29]
	v_pk_mul_f32 v[58:59], v[4:5], v[28:29]
	v_pk_fma_f32 v[56:57], v[2:3], v[30:31], v[56:57]
	v_pk_fma_f32 v[58:59], v[6:7], v[30:31], v[58:59]
	v_add_f32_e32 v72, v56, v57
	v_add_f32_e32 v73, v58, v59
	v_pk_mul_f32 v[64:65], v[40:41], v[50:51] op_sel:[0,1] op_sel_hi:[1,1]
	v_pk_mul_f32 v[68:69], v[40:41], v[54:55] op_sel:[0,1] op_sel_hi:[1,1]
	v_add_f32_dpp v74, v73, v72 row_mirror row_mask:0xf bank_mask:0xf bound_ctrl:1
	v_pk_mul_f32 v[66:67], v[42:43], v[50:51] op_sel:[0,1] op_sel_hi:[1,1]
	v_pk_mul_f32 v[70:71], v[42:43], v[54:55] op_sel:[0,1] op_sel_hi:[1,1]
	v_add_f32_dpp v74, v74, v74 quad_perm:[1,0,3,2] row_mask:0xf bank_mask:0xf bound_ctrl:1
	v_pk_fma_f32 v[0:1], v[0:1], v[32:33], v[64:65]
	v_pk_fma_f32 v[4:5], v[4:5], v[32:33], v[68:69]
	v_add_f32_dpp v74, v74, v74 quad_perm:[2,3,0,1] row_mask:0xf bank_mask:0xf bound_ctrl:1
	v_pk_fma_f32 v[2:3], v[2:3], v[34:35], v[66:67]
	v_pk_fma_f32 v[6:7], v[6:7], v[34:35], v[70:71]
	v_add_f32_dpp v74, v74, v74 row_half_mirror row_mask:0xf bank_mask:0xf bound_ctrl:1
	v_pk_fma_f32 v[0:1], v[36:37], v[74:75], v[0:1] op_sel_hi:[1,0,1]
	v_pk_fma_f32 v[2:3], v[38:39], v[74:75], v[2:3] op_sel_hi:[1,0,1]
	v_mov_b32_dpp v76, v74 row_mirror row_mask:0xf bank_mask:0xf bound_ctrl:1
	v_pk_mul_f32 v[60:61], v[0:1], v[44:45]
	v_pk_fma_f32 v[4:5], v[36:37], v[76:77], v[4:5] op_sel_hi:[1,0,1]
	v_pk_fma_f32 v[6:7], v[38:39], v[76:77], v[6:7] op_sel_hi:[1,0,1]
	v_pk_fma_f32 v[60:61], v[2:3], v[46:47], v[60:61]
	v_pk_mul_f32 v[62:63], v[4:5], v[44:45]
	v_pk_fma_f32 v[62:63], v[6:7], v[46:47], v[62:63]
	v_add_f32_e32 v113, v60, v61
	v_add_f32_e32 v95, v62, v63
	v_add_f32_dpp v84, v114, v98 row_mirror row_mask:0xf bank_mask:0x3 bound_ctrl:1
	v_add_f32_dpp v84, v122, v106 row_mirror row_mask:0xf bank_mask:0xc bound_ctrl:1
; DEV void scan_tile(const Params& p, int l, int tile, char* smem) {
;     ...
;         const f32x4 yA = S0 * o.r0 + S1 * o.r1;
;         const float y = red8((yA[0] + yA[1]) + (yA[2] + yA[3]));
;         ykeep = (cg == (sl & 7)) ? y : ykeep;
;       };
;       ScanOps oa, ob;
;       ldops(oa, 0);
; #pragma unroll
;       for (int s8 = 0; s8 < 32; s8 += 8) {
; #pragma unroll
;         for (int q = 0; q < 8; q += 2) {
;           ldops(ob, s8 + q + 1);
;           step(oa, s8 + q);
;           ldops(oa, (s8 + q + 2) & 31);
;           step(ob, s8 + q + 1);
;         }
;         yw[s8 * 32] = ykeep;
;       }
;     } else {
;       const int pw = w - 4;
;       if (ch > 0) flush(ch - 1, buf ^ 1, tid - 256);
;       if (ch + 1 < 136) produce(ch + 1, buf ^ 1, pw, 4);
;     }
;     __syncthreads();
	v_add_f32_dpp v85, v115, v99 row_mirror row_mask:0xf bank_mask:0x3 bound_ctrl:1
	v_add_f32_dpp v85, v123, v107 row_mirror row_mask:0xf bank_mask:0xc bound_ctrl:1
	v_add_f32_dpp v86, v116, v100 row_mirror row_mask:0xf bank_mask:0x3 bound_ctrl:1
	v_add_f32_dpp v86, v124, v108 row_mirror row_mask:0xf bank_mask:0xc bound_ctrl:1
	v_add_f32_dpp v87, v117, v101 row_mirror row_mask:0xf bank_mask:0x3 bound_ctrl:1
	v_add_f32_dpp v87, v125, v109 row_mirror row_mask:0xf bank_mask:0xc bound_ctrl:1
	v_add_f32_dpp v88, v118, v102 row_mirror row_mask:0xf bank_mask:0x3 bound_ctrl:1
	v_add_f32_dpp v88, v126, v110 row_mirror row_mask:0xf bank_mask:0xc bound_ctrl:1
	v_add_f32_dpp v89, v119, v103 row_mirror row_mask:0xf bank_mask:0x3 bound_ctrl:1
	v_add_f32_dpp v89, v127, v111 row_mirror row_mask:0xf bank_mask:0xc bound_ctrl:1
	v_add_f32_dpp v90, v120, v104 row_mirror row_mask:0xf bank_mask:0x3 bound_ctrl:1
	v_add_f32_dpp v90, v94, v112 row_mirror row_mask:0xf bank_mask:0xc bound_ctrl:1
	v_add_f32_dpp v91, v121, v105 row_mirror row_mask:0xf bank_mask:0x3 bound_ctrl:1
	v_add_f32_dpp v91, v95, v113 row_mirror row_mask:0xf bank_mask:0xc bound_ctrl:1
	v_add_f32_dpp v114, v98, v114 row_mirror row_mask:0xf bank_mask:0x3 bound_ctrl:1
	v_add_f32_dpp v114, v106, v122 row_mirror row_mask:0xf bank_mask:0xc bound_ctrl:1
	v_add_f32_dpp v115, v99, v115 row_mirror row_mask:0xf bank_mask:0x3 bound_ctrl:1
	v_add_f32_dpp v115, v107, v123 row_mirror row_mask:0xf bank_mask:0xc bound_ctrl:1
	v_add_f32_dpp v116, v100, v116 row_mirror row_mask:0xf bank_mask:0x3 bound_ctrl:1
	v_add_f32_dpp v116, v108, v124 row_mirror row_mask:0xf bank_mask:0xc bound_ctrl:1
	v_add_f32_dpp v117, v101, v117 row_mirror row_mask:0xf bank_mask:0x3 bound_ctrl:1
	v_add_f32_dpp v117, v109, v125 row_mirror row_mask:0xf bank_mask:0xc bound_ctrl:1
	v_add_f32_dpp v118, v102, v118 row_mirror row_mask:0xf bank_mask:0x3 bound_ctrl:1
	v_add_f32_dpp v118, v110, v126 row_mirror row_mask:0xf bank_mask:0xc bound_ctrl:1
	v_add_f32_dpp v119, v103, v119 row_mirror row_mask:0xf bank_mask:0x3 bound_ctrl:1
	v_add_f32_dpp v119, v111, v127 row_mirror row_mask:0xf bank_mask:0xc bound_ctrl:1
	v_add_f32_dpp v120, v104, v120 row_mirror row_mask:0xf bank_mask:0x3 bound_ctrl:1
	v_add_f32_dpp v120, v112, v94 row_mirror row_mask:0xf bank_mask:0xc bound_ctrl:1
	v_add_f32_dpp v121, v105, v121 row_mirror row_mask:0xf bank_mask:0x3 bound_ctrl:1
	v_add_f32_dpp v121, v113, v95 row_mirror row_mask:0xf bank_mask:0xc bound_ctrl:1
	v_add_f32_dpp v84, v84, v84 row_half_mirror row_mask:0xf bank_mask:0x5 bound_ctrl:1
	v_add_f32_dpp v84, v88, v88 row_half_mirror row_mask:0xf bank_mask:0xa bound_ctrl:1
	v_add_f32_dpp v85, v85, v85 row_half_mirror row_mask:0xf bank_mask:0x5 bound_ctrl:1
	v_add_f32_dpp v85, v89, v89 row_half_mirror row_mask:0xf bank_mask:0xa bound_ctrl:1
	v_add_f32_dpp v86, v86, v86 row_half_mirror row_mask:0xf bank_mask:0x5 bound_ctrl:1
	v_add_f32_dpp v86, v90, v90 row_half_mirror row_mask:0xf bank_mask:0xa bound_ctrl:1
	v_add_f32_dpp v87, v87, v87 row_half_mirror row_mask:0xf bank_mask:0x5 bound_ctrl:1
	v_add_f32_dpp v87, v91, v91 row_half_mirror row_mask:0xf bank_mask:0xa bound_ctrl:1
	v_add_f32_dpp v84, v84, v84 quad_perm:[2,3,0,1] row_mask:0xf bank_mask:0xf bound_ctrl:1
	v_add_f32_dpp v85, v85, v85 quad_perm:[2,3,0,1] row_mask:0xf bank_mask:0xf bound_ctrl:1
	v_add_f32_dpp v86, v86, v86 quad_perm:[2,3,0,1] row_mask:0xf bank_mask:0xf bound_ctrl:1
	v_add_f32_dpp v87, v87, v87 quad_perm:[2,3,0,1] row_mask:0xf bank_mask:0xf bound_ctrl:1
	v_cndmask_b32_e64 v88, v86, v84, s[62:63]
	v_cndmask_b32_e64 v89, v87, v85, s[62:63]
	s_nop 0
	v_add_f32_dpp v88, v88, v88 quad_perm:[1,0,3,2] row_mask:0xf bank_mask:0xf bound_ctrl:1
	v_add_f32_dpp v89, v89, v89 quad_perm:[1,0,3,2] row_mask:0xf bank_mask:0xf bound_ctrl:1
	v_cndmask_b32_e64 v90, v89, v88, s[64:65]
	ds_write_b32 v80, v90 offset:2048
	v_add_f32_dpp v114, v114, v114 row_half_mirror row_mask:0xf bank_mask:0x5 bound_ctrl:1
	v_add_f32_dpp v114, v118, v118 row_half_mirror row_mask:0xf bank_mask:0xa bound_ctrl:1
	v_add_f32_dpp v115, v115, v115 row_half_mirror row_mask:0xf bank_mask:0x5 bound_ctrl:1
	v_add_f32_dpp v115, v119, v119 row_half_mirror row_mask:0xf bank_mask:0xa bound_ctrl:1
	v_add_f32_dpp v116, v116, v116 row_half_mirror row_mask:0xf bank_mask:0x5 bound_ctrl:1
	v_add_f32_dpp v116, v120, v120 row_half_mirror row_mask:0xf bank_mask:0xa bound_ctrl:1
	v_add_f32_dpp v117, v117, v117 row_half_mirror row_mask:0xf bank_mask:0x5 bound_ctrl:1
	v_add_f32_dpp v117, v121, v121 row_half_mirror row_mask:0xf bank_mask:0xa bound_ctrl:1
	v_add_f32_dpp v114, v114, v114 quad_perm:[2,3,0,1] row_mask:0xf bank_mask:0xf bound_ctrl:1
	v_add_f32_dpp v115, v115, v115 quad_perm:[2,3,0,1] row_mask:0xf bank_mask:0xf bound_ctrl:1
	v_add_f32_dpp v116, v116, v116 quad_perm:[2,3,0,1] row_mask:0xf bank_mask:0xf bound_ctrl:1
	v_add_f32_dpp v117, v117, v117 quad_perm:[2,3,0,1] row_mask:0xf bank_mask:0xf bound_ctrl:1
	v_cndmask_b32_e64 v118, v116, v114, s[62:63]
	v_cndmask_b32_e64 v119, v117, v115, s[62:63]
	s_nop 0
	v_add_f32_dpp v118, v118, v118 quad_perm:[1,0,3,2] row_mask:0xf bank_mask:0xf bound_ctrl:1
	v_add_f32_dpp v119, v119, v119 quad_perm:[1,0,3,2] row_mask:0xf bank_mask:0xf bound_ctrl:1
	v_cndmask_b32_e64 v120, v119, v118, s[64:65]
	ds_write_b32 v82, v120 offset:2048
	v_xor_b32_e32 v78, 0xc000, v78
	v_xor_b32_e32 v79, 0xc000, v79
	v_xor_b32_e32 v81, 0xc000, v81
	v_xor_b32_e32 v80, 0x1000, v80
	v_xor_b32_e32 v82, 0x1000, v82
	s_add_u32 s46, s46, 1
	s_cmp_lt_u32 s46, 136
	s_waitcnt lgkmcnt(0)
	s_barrier
	s_cbranch_scc1 .Lsc_cloop
	s_branch .LBB0_192
